# P4 epilogue: sigmoids of the next 5 steps computed ahead of their combine so the first ring loads land under them
# baseline (speedup 1.0000x reference)
; __device__ __forceinline__ unsigned cvt_pk_bf16(float lo, float hi) { unsigned r; asm volatile("v_cvt_pk_bf16_f32 %0, %1, %2" : "=v"(r) : "v"(lo), "v"(hi)); return r; }
;     __device__ __forceinline__ void operator()(const f32x4 (&acc)[2][2][4][2], const Unit& u, int wr, int wc, int fr, int fq) const {
;         const int row0 = u.pm * BM + wr * 64 + fr, col0 = u.pn * BM + wc * 32 + 8 * fq;
;         const float GATE_DEQ = YA8_R * qr[1] * (1.0f / (::Q8 * ::Q8));
;         f32x4 bv[2][2];
; #pragma unroll
;         for (int bj = 0; bj < 2; ++bj)
; #pragma unroll
;             for (int n = 0; n < 2; ++n) bv[bj][n] = *(const f32x4*)(bias + col0 + bj * HALF + 4 * n);
; #pragma unroll
;         for (int ai = 0; ai < 2; ++ai)
; #pragma unroll
;             for (int m = 0; m < 4; ++m) { const int row = row0 + ai * HALF + m * 16; const size_t off = (size_t)row * EI + col0;
;                 const size_t offy = ((size_t)((row >> 13) * NG + (col0 >> 4)) * SEQ + (row & (SEQ - 1))) * 16 + (col0 & 15);
; #pragma unroll
;                 for (int bj = 0; bj < 2; ++bj) { const u32x4 yv = *(const u32x4*)(YA + offy + (size_t)bj * 8 * SEQ * 16), zv = *(const u32x4*)(SZ + off + bj * HALF);
;                     const i32x4 q0 = __builtin_bit_cast(i32x4, acc[ai][bj][m][0]), q1 = __builtin_bit_cast(i32x4, acc[ai][bj][m][1]);
;                     const f32x4 g0 = (f32x4){(float)q0[0], (float)q0[1], (float)q0[2], (float)q0[3]} * GATE_DEQ + bv[bj][0], g1 = (f32x4){(float)q1[0], (float)q1[1], (float)q1[2], (float)q1[3]} * GATE_DEQ + bv[bj][1];
;                     float o[8];
;                     o[0] = bf_lo(yv.x) * bf_lo(zv.x) * fast_sigmoid(g0[0]); o[1] = bf_hi(yv.x) * bf_hi(zv.x) * fast_sigmoid(g0[1]);
;                     o[2] = bf_lo(yv.y) * bf_lo(zv.y) * fast_sigmoid(g0[2]); o[3] = bf_hi(yv.y) * bf_hi(zv.y) * fast_sigmoid(g0[3]);
;                     o[4] = bf_lo(yv.z) * bf_lo(zv.z) * fast_sigmoid(g1[0]); o[5] = bf_hi(yv.z) * bf_hi(zv.z) * fast_sigmoid(g1[1]);
;                     o[6] = bf_lo(yv.w) * bf_lo(zv.w) * fast_sigmoid(g1[2]); o[7] = bf_hi(yv.w) * bf_hi(zv.w) * fast_sigmoid(g1[3]);
;                     u32x4 w; w.x = cvt_pk_bf16(o[0], o[1]); w.y = cvt_pk_bf16(o[2], o[3]); w.z = cvt_pk_bf16(o[4], o[5]); w.w = cvt_pk_bf16(o[6], o[7]);
;                     *(u32x4*)(V + off + bj * HALF) = w; } }
.LBB0_502:
	v_lshl_add_u32 v187, s52, 8, v225
	global_load_dword v186, v201, s[22:23]
	v_lshlrev_b32_e32 v188, 2, v187
	s_lshl_b32 s41, s86, 8
	global_load_dwordx4 v[68:71], v188, s[20:21]
	global_load_dwordx4 v[64:67], v188, s[20:21] offset:16
	global_load_dwordx4 v[136:139], v188, s[20:21] offset:512
	global_load_dwordx4 v[140:143], v188, s[20:21] offset:528
	s_add_i32 s41, s41, s75
	v_or_b32_e32 v189, s41, v220
	s_ashr_i32 s41, s41, 4
	v_ashrrev_i32_e32 v190, 4, v187
	s_and_b32 s41, s41, 0xfffffe00
	v_lshlrev_b32_e32 v191, 5, v189
	v_add_u32_e32 v190, s41, v190
	v_and_b32_e32 v191, 0x3f9e0, v191
	v_lshlrev_b32_e32 v190, 18, v190
	v_add3_u32 v184, v190, v191, v206
	v_lshlrev_b32_e32 v191, 1, v187
	v_lshl_add_u32 v239, v189, 14, v191
	v_add_u32_e32 v184, 0x800, v184
	v_mov_b32_e32 v207, v201
	v_add_u32_e32 v185, 0x200000, v184
	s_mov_b64 s[98:99], s[12:13]
	global_load_dwordx4 v[148:151], v239, s[98:99]
	global_load_dwordx4 v[144:147], v184, s[10:11] offset:-2048
	global_load_dwordx4 v[156:159], v239, s[98:99] offset:256
	global_load_dwordx4 v[152:155], v185, s[10:11] offset:-2048
	s_add_u32 s98, s12, 0x40000
	s_addc_u32 s99, s13, 0
	global_load_dwordx4 v[164:167], v239, s[98:99]
	global_load_dwordx4 v[160:163], v184, s[10:11] offset:-1536
	global_load_dwordx4 v[180:183], v239, s[98:99] offset:256
	global_load_dwordx4 v[172:175], v185, s[10:11] offset:-1536
	s_add_u32 s98, s12, 0x80000
	s_addc_u32 s99, s13, 0
	global_load_dwordx4 v[244:247], v239, s[98:99]
	global_load_dwordx4 v[240:243], v184, s[10:11] offset:-1024
	global_load_dwordx4 v[176:179], v239, s[98:99] offset:256
	global_load_dwordx4 v[248:251], v185, s[10:11] offset:-1024
	s_waitcnt vmcnt(12)
	v_mul_f32_e32 v186, 0x41600000, v186
	v_mul_f32_e32 v186, 0x38800200, v186
	s_mov_b32 s32, 0xbfb8aa3b
	v_cvt_f32_i32_e32 v60, v60
	v_cvt_f32_i32_e32 v61, v61
	v_cvt_f32_i32_e32 v62, v62
	v_cvt_f32_i32_e32 v63, v63
	v_cvt_f32_i32_e32 v56, v56
	v_cvt_f32_i32_e32 v57, v57
	v_cvt_f32_i32_e32 v58, v58
	v_cvt_f32_i32_e32 v59, v59
	v_pk_fma_f32 v[60:61], v[186:187], v[60:61], v[68:69] op_sel_hi:[0,1,1]
	v_pk_fma_f32 v[62:63], v[186:187], v[62:63], v[70:71] op_sel_hi:[0,1,1]
	v_pk_fma_f32 v[56:57], v[186:187], v[56:57], v[64:65] op_sel_hi:[0,1,1]
	v_pk_fma_f32 v[58:59], v[186:187], v[58:59], v[66:67] op_sel_hi:[0,1,1]
	v_pk_mul_f32 v[60:61], v[60:61], s[32:33] op_sel_hi:[1,0]
	v_pk_mul_f32 v[62:63], v[62:63], s[32:33] op_sel_hi:[1,0]
	v_pk_mul_f32 v[56:57], v[56:57], s[32:33] op_sel_hi:[1,0]
	v_pk_mul_f32 v[58:59], v[58:59], s[32:33] op_sel_hi:[1,0]
	v_exp_f32_e32 v60, v60
	v_exp_f32_e32 v61, v61
	v_exp_f32_e32 v62, v62
	v_exp_f32_e32 v63, v63
	v_exp_f32_e32 v56, v56
	v_exp_f32_e32 v57, v57
	v_exp_f32_e32 v58, v58
	v_exp_f32_e32 v59, v59
	v_pk_add_f32 v[60:61], v[60:61], 1.0 op_sel_hi:[1,0]
	v_pk_add_f32 v[62:63], v[62:63], 1.0 op_sel_hi:[1,0]
	v_pk_add_f32 v[56:57], v[56:57], 1.0 op_sel_hi:[1,0]
	v_pk_add_f32 v[58:59], v[58:59], 1.0 op_sel_hi:[1,0]
	v_rcp_f32_e32 v60, v60
	v_rcp_f32_e32 v61, v61
	v_rcp_f32_e32 v62, v62
	v_rcp_f32_e32 v63, v63
	v_rcp_f32_e32 v56, v56
	v_rcp_f32_e32 v57, v57
	v_rcp_f32_e32 v58, v58
	v_rcp_f32_e32 v59, v59
	v_cvt_f32_i32_e32 v132, v132
	v_cvt_f32_i32_e32 v133, v133
	v_cvt_f32_i32_e32 v134, v134
	v_cvt_f32_i32_e32 v135, v135
	v_cvt_f32_i32_e32 v128, v128
	v_cvt_f32_i32_e32 v129, v129
	v_cvt_f32_i32_e32 v130, v130
	v_cvt_f32_i32_e32 v131, v131
	v_pk_fma_f32 v[132:133], v[186:187], v[132:133], v[136:137] op_sel_hi:[0,1,1]
	v_pk_fma_f32 v[134:135], v[186:187], v[134:135], v[138:139] op_sel_hi:[0,1,1]
	v_pk_fma_f32 v[128:129], v[186:187], v[128:129], v[140:141] op_sel_hi:[0,1,1]
	v_pk_fma_f32 v[130:131], v[186:187], v[130:131], v[142:143] op_sel_hi:[0,1,1]
	v_pk_mul_f32 v[132:133], v[132:133], s[32:33] op_sel_hi:[1,0]
	v_pk_mul_f32 v[134:135], v[134:135], s[32:33] op_sel_hi:[1,0]
	v_pk_mul_f32 v[128:129], v[128:129], s[32:33] op_sel_hi:[1,0]
	v_pk_mul_f32 v[130:131], v[130:131], s[32:33] op_sel_hi:[1,0]
	v_exp_f32_e32 v132, v132
	v_exp_f32_e32 v133, v133
	v_exp_f32_e32 v134, v134
	v_exp_f32_e32 v135, v135
	v_exp_f32_e32 v128, v128
	v_exp_f32_e32 v129, v129
	v_exp_f32_e32 v130, v130
	v_exp_f32_e32 v131, v131
	v_pk_add_f32 v[132:133], v[132:133], 1.0 op_sel_hi:[1,0]
	v_pk_add_f32 v[134:135], v[134:135], 1.0 op_sel_hi:[1,0]
	v_pk_add_f32 v[128:129], v[128:129], 1.0 op_sel_hi:[1,0]
	v_pk_add_f32 v[130:131], v[130:131], 1.0 op_sel_hi:[1,0]
	v_rcp_f32_e32 v132, v132
	v_rcp_f32_e32 v133, v133
	v_rcp_f32_e32 v134, v134
	v_rcp_f32_e32 v135, v135
	v_rcp_f32_e32 v128, v128
	v_rcp_f32_e32 v129, v129
	v_rcp_f32_e32 v130, v130
	v_rcp_f32_e32 v131, v131
	v_cvt_f32_i32_e32 v124, v124
	v_cvt_f32_i32_e32 v125, v125
	v_cvt_f32_i32_e32 v126, v126
	v_cvt_f32_i32_e32 v127, v127
	v_cvt_f32_i32_e32 v120, v120
	v_cvt_f32_i32_e32 v121, v121
	v_cvt_f32_i32_e32 v122, v122
	v_cvt_f32_i32_e32 v123, v123
	v_pk_fma_f32 v[124:125], v[186:187], v[124:125], v[68:69] op_sel_hi:[0,1,1]
	v_pk_fma_f32 v[126:127], v[186:187], v[126:127], v[70:71] op_sel_hi:[0,1,1]
	v_pk_fma_f32 v[120:121], v[186:187], v[120:121], v[64:65] op_sel_hi:[0,1,1]
	v_pk_fma_f32 v[122:123], v[186:187], v[122:123], v[66:67] op_sel_hi:[0,1,1]
	v_pk_mul_f32 v[124:125], v[124:125], s[32:33] op_sel_hi:[1,0]
	v_pk_mul_f32 v[126:127], v[126:127], s[32:33] op_sel_hi:[1,0]
	v_pk_mul_f32 v[120:121], v[120:121], s[32:33] op_sel_hi:[1,0]
	v_pk_mul_f32 v[122:123], v[122:123], s[32:33] op_sel_hi:[1,0]
	v_exp_f32_e32 v124, v124
	v_exp_f32_e32 v125, v125
	v_exp_f32_e32 v126, v126
	v_exp_f32_e32 v127, v127
	v_exp_f32_e32 v120, v120
	v_exp_f32_e32 v121, v121
	v_exp_f32_e32 v122, v122
	v_exp_f32_e32 v123, v123
	v_pk_add_f32 v[124:125], v[124:125], 1.0 op_sel_hi:[1,0]
; __device__ __forceinline__ unsigned cvt_pk_bf16(float lo, float hi) { unsigned r; asm volatile("v_cvt_pk_bf16_f32 %0, %1, %2" : "=v"(r) : "v"(lo), "v"(hi)); return r; }
; __device__ __forceinline__ float bf_lo(unsigned w) { return __uint_as_float(w << 16); }
; __device__ __forceinline__ float bf_hi(unsigned w) { return __uint_as_float(w & 0xffff0000u); }
; __device__ __forceinline__ float fast_sigmoid(float x) { return __builtin_amdgcn_rcpf(1.0f + __builtin_amdgcn_exp2f(-1.4426950408889634f * x)); }
;     __device__ __forceinline__ void operator()(const f32x4 (&acc)[2][2][4][2], const Unit& u, int wr, int wc, int fr, int fq) const {
;     ...
;                 for (int bj = 0; bj < 2; ++bj) { const u32x4 yv = *(const u32x4*)(YA + offy + (size_t)bj * 8 * SEQ * 16), zv = *(const u32x4*)(SZ + off + bj * HALF);
;                     const i32x4 q0 = __builtin_bit_cast(i32x4, acc[ai][bj][m][0]), q1 = __builtin_bit_cast(i32x4, acc[ai][bj][m][1]);
;                     const f32x4 g0 = (f32x4){(float)q0[0], (float)q0[1], (float)q0[2], (float)q0[3]} * GATE_DEQ + bv[bj][0], g1 = (f32x4){(float)q1[0], (float)q1[1], (float)q1[2], (float)q1[3]} * GATE_DEQ + bv[bj][1];
;                     float o[8];
;                     o[0] = bf_lo(yv.x) * bf_lo(zv.x) * fast_sigmoid(g0[0]); o[1] = bf_hi(yv.x) * bf_hi(zv.x) * fast_sigmoid(g0[1]);
;                     o[2] = bf_lo(yv.y) * bf_lo(zv.y) * fast_sigmoid(g0[2]); o[3] = bf_hi(yv.y) * bf_hi(zv.y) * fast_sigmoid(g0[3]);
;                     o[4] = bf_lo(yv.z) * bf_lo(zv.z) * fast_sigmoid(g1[0]); o[5] = bf_hi(yv.z) * bf_hi(zv.z) * fast_sigmoid(g1[1]);
;                     o[6] = bf_lo(yv.w) * bf_lo(zv.w) * fast_sigmoid(g1[2]); o[7] = bf_hi(yv.w) * bf_hi(zv.w) * fast_sigmoid(g1[3]);
;                     u32x4 w; w.x = cvt_pk_bf16(o[0], o[1]); w.y = cvt_pk_bf16(o[2], o[3]); w.z = cvt_pk_bf16(o[4], o[5]); w.w = cvt_pk_bf16(o[6], o[7]);
;                     *(u32x4*)(V + off + bj * HALF) = w; } }
	v_pk_add_f32 v[126:127], v[126:127], 1.0 op_sel_hi:[1,0]
	v_pk_add_f32 v[120:121], v[120:121], 1.0 op_sel_hi:[1,0]
	v_pk_add_f32 v[122:123], v[122:123], 1.0 op_sel_hi:[1,0]
	v_rcp_f32_e32 v124, v124
	v_rcp_f32_e32 v125, v125
	v_rcp_f32_e32 v126, v126
	v_rcp_f32_e32 v127, v127
	v_rcp_f32_e32 v120, v120
	v_rcp_f32_e32 v121, v121
	v_rcp_f32_e32 v122, v122
	v_rcp_f32_e32 v123, v123
	v_cvt_f32_i32_e32 v116, v116
	v_cvt_f32_i32_e32 v117, v117
	v_cvt_f32_i32_e32 v118, v118
	v_cvt_f32_i32_e32 v119, v119
	v_cvt_f32_i32_e32 v112, v112
	v_cvt_f32_i32_e32 v113, v113
	v_cvt_f32_i32_e32 v114, v114
	v_cvt_f32_i32_e32 v115, v115
	v_pk_fma_f32 v[116:117], v[186:187], v[116:117], v[136:137] op_sel_hi:[0,1,1]
	v_pk_fma_f32 v[118:119], v[186:187], v[118:119], v[138:139] op_sel_hi:[0,1,1]
	v_pk_fma_f32 v[112:113], v[186:187], v[112:113], v[140:141] op_sel_hi:[0,1,1]
	v_pk_fma_f32 v[114:115], v[186:187], v[114:115], v[142:143] op_sel_hi:[0,1,1]
	v_pk_mul_f32 v[116:117], v[116:117], s[32:33] op_sel_hi:[1,0]
	v_pk_mul_f32 v[118:119], v[118:119], s[32:33] op_sel_hi:[1,0]
	v_pk_mul_f32 v[112:113], v[112:113], s[32:33] op_sel_hi:[1,0]
	v_pk_mul_f32 v[114:115], v[114:115], s[32:33] op_sel_hi:[1,0]
	v_exp_f32_e32 v116, v116
	v_exp_f32_e32 v117, v117
	v_exp_f32_e32 v118, v118
	v_exp_f32_e32 v119, v119
	v_exp_f32_e32 v112, v112
	v_exp_f32_e32 v113, v113
	v_exp_f32_e32 v114, v114
	v_exp_f32_e32 v115, v115
	v_pk_add_f32 v[116:117], v[116:117], 1.0 op_sel_hi:[1,0]
	v_pk_add_f32 v[118:119], v[118:119], 1.0 op_sel_hi:[1,0]
	v_pk_add_f32 v[112:113], v[112:113], 1.0 op_sel_hi:[1,0]
	v_pk_add_f32 v[114:115], v[114:115], 1.0 op_sel_hi:[1,0]
	v_rcp_f32_e32 v116, v116
	v_rcp_f32_e32 v117, v117
	v_rcp_f32_e32 v118, v118
	v_rcp_f32_e32 v119, v119
	v_rcp_f32_e32 v112, v112
	v_rcp_f32_e32 v113, v113
	v_rcp_f32_e32 v114, v114
	v_rcp_f32_e32 v115, v115
	v_cvt_f32_i32_e32 v108, v108
	v_cvt_f32_i32_e32 v109, v109
	v_cvt_f32_i32_e32 v110, v110
	v_cvt_f32_i32_e32 v111, v111
	v_cvt_f32_i32_e32 v104, v104
	v_cvt_f32_i32_e32 v105, v105
	v_cvt_f32_i32_e32 v106, v106
	v_cvt_f32_i32_e32 v107, v107
	v_pk_fma_f32 v[108:109], v[186:187], v[108:109], v[68:69] op_sel_hi:[0,1,1]
	v_pk_fma_f32 v[110:111], v[186:187], v[110:111], v[70:71] op_sel_hi:[0,1,1]
	v_pk_fma_f32 v[104:105], v[186:187], v[104:105], v[64:65] op_sel_hi:[0,1,1]
	v_pk_fma_f32 v[106:107], v[186:187], v[106:107], v[66:67] op_sel_hi:[0,1,1]
	v_pk_mul_f32 v[108:109], v[108:109], s[32:33] op_sel_hi:[1,0]
	v_pk_mul_f32 v[110:111], v[110:111], s[32:33] op_sel_hi:[1,0]
	v_pk_mul_f32 v[104:105], v[104:105], s[32:33] op_sel_hi:[1,0]
	v_pk_mul_f32 v[106:107], v[106:107], s[32:33] op_sel_hi:[1,0]
	v_exp_f32_e32 v108, v108
	v_exp_f32_e32 v109, v109
	v_exp_f32_e32 v110, v110
	v_exp_f32_e32 v111, v111
	v_exp_f32_e32 v104, v104
	v_exp_f32_e32 v105, v105
	v_exp_f32_e32 v106, v106
	v_exp_f32_e32 v107, v107
	v_pk_add_f32 v[108:109], v[108:109], 1.0 op_sel_hi:[1,0]
	v_pk_add_f32 v[110:111], v[110:111], 1.0 op_sel_hi:[1,0]
	v_pk_add_f32 v[104:105], v[104:105], 1.0 op_sel_hi:[1,0]
	v_pk_add_f32 v[106:107], v[106:107], 1.0 op_sel_hi:[1,0]
	v_rcp_f32_e32 v108, v108
	v_rcp_f32_e32 v109, v109
	v_rcp_f32_e32 v110, v110
	v_rcp_f32_e32 v111, v111
	v_rcp_f32_e32 v104, v104
	v_rcp_f32_e32 v105, v105
	v_rcp_f32_e32 v106, v106
	v_rcp_f32_e32 v107, v107
	v_cvt_f32_i32_e32 v100, v100
	v_cvt_f32_i32_e32 v101, v101
	v_cvt_f32_i32_e32 v102, v102
	v_cvt_f32_i32_e32 v103, v103
	v_cvt_f32_i32_e32 v96, v96
	v_cvt_f32_i32_e32 v97, v97
	v_cvt_f32_i32_e32 v98, v98
	v_cvt_f32_i32_e32 v99, v99
	v_pk_fma_f32 v[100:101], v[186:187], v[100:101], v[136:137] op_sel_hi:[0,1,1]
	v_pk_fma_f32 v[102:103], v[186:187], v[102:103], v[138:139] op_sel_hi:[0,1,1]
	v_pk_fma_f32 v[96:97], v[186:187], v[96:97], v[140:141] op_sel_hi:[0,1,1]
	v_pk_fma_f32 v[98:99], v[186:187], v[98:99], v[142:143] op_sel_hi:[0,1,1]
	v_pk_mul_f32 v[100:101], v[100:101], s[32:33] op_sel_hi:[1,0]
	v_pk_mul_f32 v[102:103], v[102:103], s[32:33] op_sel_hi:[1,0]
	v_pk_mul_f32 v[96:97], v[96:97], s[32:33] op_sel_hi:[1,0]
	v_pk_mul_f32 v[98:99], v[98:99], s[32:33] op_sel_hi:[1,0]
	v_exp_f32_e32 v100, v100
	v_exp_f32_e32 v101, v101
	v_exp_f32_e32 v102, v102
	v_exp_f32_e32 v103, v103
	v_exp_f32_e32 v96, v96
	v_exp_f32_e32 v97, v97
	v_exp_f32_e32 v98, v98
	v_exp_f32_e32 v99, v99
	v_pk_add_f32 v[100:101], v[100:101], 1.0 op_sel_hi:[1,0]
	v_pk_add_f32 v[102:103], v[102:103], 1.0 op_sel_hi:[1,0]
	v_pk_add_f32 v[96:97], v[96:97], 1.0 op_sel_hi:[1,0]
	v_pk_add_f32 v[98:99], v[98:99], 1.0 op_sel_hi:[1,0]
	v_rcp_f32_e32 v100, v100
	v_rcp_f32_e32 v101, v101
	v_rcp_f32_e32 v102, v102
	v_rcp_f32_e32 v103, v103
	v_rcp_f32_e32 v96, v96
	v_rcp_f32_e32 v97, v97
	v_rcp_f32_e32 v98, v98
	v_rcp_f32_e32 v99, v99
	s_waitcnt vmcnt(10)
; __device__ __forceinline__ unsigned cvt_pk_bf16(float lo, float hi) { unsigned r; asm volatile("v_cvt_pk_bf16_f32 %0, %1, %2" : "=v"(r) : "v"(lo), "v"(hi)); return r; }
; __device__ __forceinline__ float bf_lo(unsigned w) { return __uint_as_float(w << 16); }
; __device__ __forceinline__ float bf_hi(unsigned w) { return __uint_as_float(w & 0xffff0000u); }
; __device__ __forceinline__ float fast_sigmoid(float x) { return __builtin_amdgcn_rcpf(1.0f + __builtin_amdgcn_exp2f(-1.4426950408889634f * x)); }
;     __device__ __forceinline__ void operator()(const f32x4 (&acc)[2][2][4][2], const Unit& u, int wr, int wc, int fr, int fq) const {
;     ...
;                 for (int bj = 0; bj < 2; ++bj) { const u32x4 yv = *(const u32x4*)(YA + offy + (size_t)bj * 8 * SEQ * 16), zv = *(const u32x4*)(SZ + off + bj * HALF);
;                     const i32x4 q0 = __builtin_bit_cast(i32x4, acc[ai][bj][m][0]), q1 = __builtin_bit_cast(i32x4, acc[ai][bj][m][1]);
;                     const f32x4 g0 = (f32x4){(float)q0[0], (float)q0[1], (float)q0[2], (float)q0[3]} * GATE_DEQ + bv[bj][0], g1 = (f32x4){(float)q1[0], (float)q1[1], (float)q1[2], (float)q1[3]} * GATE_DEQ + bv[bj][1];
;                     float o[8];
;                     o[0] = bf_lo(yv.x) * bf_lo(zv.x) * fast_sigmoid(g0[0]); o[1] = bf_hi(yv.x) * bf_hi(zv.x) * fast_sigmoid(g0[1]);
;                     o[2] = bf_lo(yv.y) * bf_lo(zv.y) * fast_sigmoid(g0[2]); o[3] = bf_hi(yv.y) * bf_hi(zv.y) * fast_sigmoid(g0[3]);
;                     o[4] = bf_lo(yv.z) * bf_lo(zv.z) * fast_sigmoid(g1[0]); o[5] = bf_hi(yv.z) * bf_hi(zv.z) * fast_sigmoid(g1[1]);
;                     o[6] = bf_lo(yv.w) * bf_lo(zv.w) * fast_sigmoid(g1[2]); o[7] = bf_hi(yv.w) * bf_hi(zv.w) * fast_sigmoid(g1[3]);
;                     u32x4 w; w.x = cvt_pk_bf16(o[0], o[1]); w.y = cvt_pk_bf16(o[2], o[3]); w.z = cvt_pk_bf16(o[4], o[5]); w.w = cvt_pk_bf16(o[6], o[7]);
;                     *(u32x4*)(V + off + bj * HALF) = w; } }
	v_lshlrev_b32_e32 v168, 16, v144
	v_and_b32_e32 v169, 0xffff0000, v144
	v_lshlrev_b32_e32 v188, 16, v148
	v_and_b32_e32 v189, 0xffff0000, v148
	v_pk_mul_f32 v[168:169], v[168:169], v[188:189]
	v_pk_mul_f32 v[60:61], v[168:169], v[60:61]
	v_lshlrev_b32_e32 v170, 16, v145
	v_and_b32_e32 v171, 0xffff0000, v145
	v_lshlrev_b32_e32 v190, 16, v149
	v_and_b32_e32 v191, 0xffff0000, v149
	v_pk_mul_f32 v[170:171], v[170:171], v[190:191]
	v_pk_mul_f32 v[62:63], v[170:171], v[62:63]
	v_lshlrev_b32_e32 v168, 16, v146
	v_and_b32_e32 v169, 0xffff0000, v146
	v_lshlrev_b32_e32 v188, 16, v150
	v_and_b32_e32 v189, 0xffff0000, v150
	v_pk_mul_f32 v[168:169], v[168:169], v[188:189]
	v_pk_mul_f32 v[56:57], v[168:169], v[56:57]
	v_lshlrev_b32_e32 v170, 16, v147
	v_and_b32_e32 v171, 0xffff0000, v147
	v_lshlrev_b32_e32 v190, 16, v151
	v_and_b32_e32 v191, 0xffff0000, v151
	v_pk_mul_f32 v[170:171], v[170:171], v[190:191]
	v_pk_mul_f32 v[58:59], v[170:171], v[58:59]
	s_add_u32 s98, s12, 0xc0000
	s_addc_u32 s99, s13, 0
	global_load_dwordx4 v[148:151], v239, s[98:99]
	global_load_dwordx4 v[144:147], v184, s[10:11] offset:-512
	v_cvt_pk_bf16_f32 v60, v60, v61
	v_cvt_pk_bf16_f32 v61, v62, v63
	v_cvt_pk_bf16_f32 v62, v56, v57
	v_cvt_pk_bf16_f32 v63, v58, v59
	s_mov_b64 s[100:101], s[16:17]
	global_store_dwordx4 v239, v[60:63], s[100:101]
	v_cvt_f32_i32_e32 v92, v92
	v_cvt_f32_i32_e32 v93, v93
	v_cvt_f32_i32_e32 v94, v94
	v_cvt_f32_i32_e32 v95, v95
	v_cvt_f32_i32_e32 v88, v88
	v_cvt_f32_i32_e32 v89, v89
	v_cvt_f32_i32_e32 v90, v90
	v_cvt_f32_i32_e32 v91, v91
	v_pk_fma_f32 v[92:93], v[186:187], v[92:93], v[68:69] op_sel_hi:[0,1,1]
	v_pk_fma_f32 v[94:95], v[186:187], v[94:95], v[70:71] op_sel_hi:[0,1,1]
	v_pk_fma_f32 v[88:89], v[186:187], v[88:89], v[64:65] op_sel_hi:[0,1,1]
	v_pk_fma_f32 v[90:91], v[186:187], v[90:91], v[66:67] op_sel_hi:[0,1,1]
	v_pk_mul_f32 v[92:93], v[92:93], s[32:33] op_sel_hi:[1,0]
	v_pk_mul_f32 v[94:95], v[94:95], s[32:33] op_sel_hi:[1,0]
	v_pk_mul_f32 v[88:89], v[88:89], s[32:33] op_sel_hi:[1,0]
	v_pk_mul_f32 v[90:91], v[90:91], s[32:33] op_sel_hi:[1,0]
	v_exp_f32_e32 v92, v92
	v_exp_f32_e32 v93, v93
	v_exp_f32_e32 v94, v94
	v_exp_f32_e32 v95, v95
	v_exp_f32_e32 v88, v88
	v_exp_f32_e32 v89, v89
	v_exp_f32_e32 v90, v90
	v_exp_f32_e32 v91, v91
	v_pk_add_f32 v[92:93], v[92:93], 1.0 op_sel_hi:[1,0]
	v_pk_add_f32 v[94:95], v[94:95], 1.0 op_sel_hi:[1,0]
	v_pk_add_f32 v[88:89], v[88:89], 1.0 op_sel_hi:[1,0]
	v_pk_add_f32 v[90:91], v[90:91], 1.0 op_sel_hi:[1,0]
	v_rcp_f32_e32 v92, v92
	v_rcp_f32_e32 v93, v93
	v_rcp_f32_e32 v94, v94
	v_rcp_f32_e32 v95, v95
	v_rcp_f32_e32 v88, v88
	v_rcp_f32_e32 v89, v89
	v_rcp_f32_e32 v90, v90
	v_rcp_f32_e32 v91, v91
	s_waitcnt vmcnt(11)
	v_lshlrev_b32_e32 v168, 16, v152
	v_and_b32_e32 v169, 0xffff0000, v152
	v_lshlrev_b32_e32 v188, 16, v156
	v_and_b32_e32 v189, 0xffff0000, v156
	v_pk_mul_f32 v[168:169], v[168:169], v[188:189]
	v_pk_mul_f32 v[132:133], v[168:169], v[132:133]
	v_lshlrev_b32_e32 v170, 16, v153
	v_and_b32_e32 v171, 0xffff0000, v153
	v_lshlrev_b32_e32 v190, 16, v157
	v_and_b32_e32 v191, 0xffff0000, v157
	v_pk_mul_f32 v[170:171], v[170:171], v[190:191]
	v_pk_mul_f32 v[134:135], v[170:171], v[134:135]
	v_lshlrev_b32_e32 v168, 16, v154
	v_and_b32_e32 v169, 0xffff0000, v154
	v_lshlrev_b32_e32 v188, 16, v158
	v_and_b32_e32 v189, 0xffff0000, v158
	v_pk_mul_f32 v[168:169], v[168:169], v[188:189]
	v_pk_mul_f32 v[128:129], v[168:169], v[128:129]
	v_lshlrev_b32_e32 v170, 16, v155
	v_and_b32_e32 v171, 0xffff0000, v155
	v_lshlrev_b32_e32 v190, 16, v159
	v_and_b32_e32 v191, 0xffff0000, v159
	v_pk_mul_f32 v[170:171], v[170:171], v[190:191]
	v_pk_mul_f32 v[130:131], v[170:171], v[130:131]
	global_load_dwordx4 v[156:159], v239, s[98:99] offset:256
	global_load_dwordx4 v[152:155], v185, s[10:11] offset:-512
	v_cvt_pk_bf16_f32 v132, v132, v133
	v_cvt_pk_bf16_f32 v133, v134, v135
	v_cvt_pk_bf16_f32 v134, v128, v129
	v_cvt_pk_bf16_f32 v135, v130, v131
	global_store_dwordx4 v239, v[132:135], s[100:101] offset:256
	v_cvt_f32_i32_e32 v84, v84
	v_cvt_f32_i32_e32 v85, v85
	v_cvt_f32_i32_e32 v86, v86
	v_cvt_f32_i32_e32 v87, v87
	v_cvt_f32_i32_e32 v80, v80
	v_cvt_f32_i32_e32 v81, v81
	v_cvt_f32_i32_e32 v82, v82
	v_cvt_f32_i32_e32 v83, v83
	v_pk_fma_f32 v[84:85], v[186:187], v[84:85], v[136:137] op_sel_hi:[0,1,1]
	v_pk_fma_f32 v[86:87], v[186:187], v[86:87], v[138:139] op_sel_hi:[0,1,1]
	v_pk_fma_f32 v[80:81], v[186:187], v[80:81], v[140:141] op_sel_hi:[0,1,1]
	v_pk_fma_f32 v[82:83], v[186:187], v[82:83], v[142:143] op_sel_hi:[0,1,1]
	v_pk_mul_f32 v[84:85], v[84:85], s[32:33] op_sel_hi:[1,0]
	v_pk_mul_f32 v[86:87], v[86:87], s[32:33] op_sel_hi:[1,0]
	v_pk_mul_f32 v[80:81], v[80:81], s[32:33] op_sel_hi:[1,0]
	v_pk_mul_f32 v[82:83], v[82:83], s[32:33] op_sel_hi:[1,0]
	v_exp_f32_e32 v84, v84
	v_exp_f32_e32 v85, v85
	v_exp_f32_e32 v86, v86
	v_exp_f32_e32 v87, v87
	v_exp_f32_e32 v80, v80
	v_exp_f32_e32 v81, v81
	v_exp_f32_e32 v82, v82
	v_exp_f32_e32 v83, v83
	v_pk_add_f32 v[84:85], v[84:85], 1.0 op_sel_hi:[1,0]
	v_pk_add_f32 v[86:87], v[86:87], 1.0 op_sel_hi:[1,0]
	v_pk_add_f32 v[80:81], v[80:81], 1.0 op_sel_hi:[1,0]
	v_pk_add_f32 v[82:83], v[82:83], 1.0 op_sel_hi:[1,0]
	v_rcp_f32_e32 v84, v84
	v_rcp_f32_e32 v85, v85
	v_rcp_f32_e32 v86, v86
	v_rcp_f32_e32 v87, v87
	v_rcp_f32_e32 v80, v80
	v_rcp_f32_e32 v81, v81
	v_rcp_f32_e32 v82, v82
	v_rcp_f32_e32 v83, v83
	s_waitcnt vmcnt(12)
; __device__ __forceinline__ unsigned cvt_pk_bf16(float lo, float hi) { unsigned r; asm volatile("v_cvt_pk_bf16_f32 %0, %1, %2" : "=v"(r) : "v"(lo), "v"(hi)); return r; }
; __device__ __forceinline__ float bf_lo(unsigned w) { return __uint_as_float(w << 16); }
; __device__ __forceinline__ float bf_hi(unsigned w) { return __uint_as_float(w & 0xffff0000u); }
; __device__ __forceinline__ float fast_sigmoid(float x) { return __builtin_amdgcn_rcpf(1.0f + __builtin_amdgcn_exp2f(-1.4426950408889634f * x)); }
;     __device__ __forceinline__ void operator()(const f32x4 (&acc)[2][2][4][2], const Unit& u, int wr, int wc, int fr, int fq) const {
;     ...
;                 for (int bj = 0; bj < 2; ++bj) { const u32x4 yv = *(const u32x4*)(YA + offy + (size_t)bj * 8 * SEQ * 16), zv = *(const u32x4*)(SZ + off + bj * HALF);
;                     const i32x4 q0 = __builtin_bit_cast(i32x4, acc[ai][bj][m][0]), q1 = __builtin_bit_cast(i32x4, acc[ai][bj][m][1]);
;                     const f32x4 g0 = (f32x4){(float)q0[0], (float)q0[1], (float)q0[2], (float)q0[3]} * GATE_DEQ + bv[bj][0], g1 = (f32x4){(float)q1[0], (float)q1[1], (float)q1[2], (float)q1[3]} * GATE_DEQ + bv[bj][1];
;                     float o[8];
;                     o[0] = bf_lo(yv.x) * bf_lo(zv.x) * fast_sigmoid(g0[0]); o[1] = bf_hi(yv.x) * bf_hi(zv.x) * fast_sigmoid(g0[1]);
;                     o[2] = bf_lo(yv.y) * bf_lo(zv.y) * fast_sigmoid(g0[2]); o[3] = bf_hi(yv.y) * bf_hi(zv.y) * fast_sigmoid(g0[3]);
;                     o[4] = bf_lo(yv.z) * bf_lo(zv.z) * fast_sigmoid(g1[0]); o[5] = bf_hi(yv.z) * bf_hi(zv.z) * fast_sigmoid(g1[1]);
;                     o[6] = bf_lo(yv.w) * bf_lo(zv.w) * fast_sigmoid(g1[2]); o[7] = bf_hi(yv.w) * bf_hi(zv.w) * fast_sigmoid(g1[3]);
;                     u32x4 w; w.x = cvt_pk_bf16(o[0], o[1]); w.y = cvt_pk_bf16(o[2], o[3]); w.z = cvt_pk_bf16(o[4], o[5]); w.w = cvt_pk_bf16(o[6], o[7]);
;                     *(u32x4*)(V + off + bj * HALF) = w; } }
	v_lshlrev_b32_e32 v168, 16, v160
	v_and_b32_e32 v169, 0xffff0000, v160
	v_lshlrev_b32_e32 v188, 16, v164
	v_and_b32_e32 v189, 0xffff0000, v164
	v_pk_mul_f32 v[168:169], v[168:169], v[188:189]
	v_pk_mul_f32 v[124:125], v[168:169], v[124:125]
	v_lshlrev_b32_e32 v170, 16, v161
	v_and_b32_e32 v171, 0xffff0000, v161
	v_lshlrev_b32_e32 v190, 16, v165
	v_and_b32_e32 v191, 0xffff0000, v165
	v_pk_mul_f32 v[170:171], v[170:171], v[190:191]
	v_pk_mul_f32 v[126:127], v[170:171], v[126:127]
	v_lshlrev_b32_e32 v168, 16, v162
	v_and_b32_e32 v169, 0xffff0000, v162
	v_lshlrev_b32_e32 v188, 16, v166
	v_and_b32_e32 v189, 0xffff0000, v166
	v_pk_mul_f32 v[168:169], v[168:169], v[188:189]
	v_pk_mul_f32 v[120:121], v[168:169], v[120:121]
	v_lshlrev_b32_e32 v170, 16, v163
	v_and_b32_e32 v171, 0xffff0000, v163
	v_lshlrev_b32_e32 v190, 16, v167
	v_and_b32_e32 v191, 0xffff0000, v167
	v_pk_mul_f32 v[170:171], v[170:171], v[190:191]
	v_pk_mul_f32 v[122:123], v[170:171], v[122:123]
	s_add_u32 s98, s12, 0x200000
	s_addc_u32 s99, s13, 0
	global_load_dwordx4 v[164:167], v239, s[98:99]
	global_load_dwordx4 v[160:163], v184, s[10:11] offset:2048
	v_cvt_pk_bf16_f32 v124, v124, v125
	v_cvt_pk_bf16_f32 v125, v126, v127
	v_cvt_pk_bf16_f32 v126, v120, v121
	v_cvt_pk_bf16_f32 v127, v122, v123
	s_add_u32 s100, s16, 0x40000
	s_addc_u32 s101, s17, 0
	global_store_dwordx4 v239, v[124:127], s[100:101]
	v_cvt_f32_i32_e32 v76, v76
	v_cvt_f32_i32_e32 v77, v77
	v_cvt_f32_i32_e32 v78, v78
	v_cvt_f32_i32_e32 v79, v79
	v_cvt_f32_i32_e32 v72, v72
	v_cvt_f32_i32_e32 v73, v73
	v_cvt_f32_i32_e32 v74, v74
	v_cvt_f32_i32_e32 v75, v75
	v_pk_fma_f32 v[76:77], v[186:187], v[76:77], v[68:69] op_sel_hi:[0,1,1]
	v_pk_fma_f32 v[78:79], v[186:187], v[78:79], v[70:71] op_sel_hi:[0,1,1]
	v_pk_fma_f32 v[72:73], v[186:187], v[72:73], v[64:65] op_sel_hi:[0,1,1]
	v_pk_fma_f32 v[74:75], v[186:187], v[74:75], v[66:67] op_sel_hi:[0,1,1]
	v_pk_mul_f32 v[76:77], v[76:77], s[32:33] op_sel_hi:[1,0]
	v_pk_mul_f32 v[78:79], v[78:79], s[32:33] op_sel_hi:[1,0]
	v_pk_mul_f32 v[72:73], v[72:73], s[32:33] op_sel_hi:[1,0]
	v_pk_mul_f32 v[74:75], v[74:75], s[32:33] op_sel_hi:[1,0]
	v_exp_f32_e32 v76, v76
	v_exp_f32_e32 v77, v77
	v_exp_f32_e32 v78, v78
	v_exp_f32_e32 v79, v79
	v_exp_f32_e32 v72, v72
	v_exp_f32_e32 v73, v73
	v_exp_f32_e32 v74, v74
	v_exp_f32_e32 v75, v75
	v_pk_add_f32 v[76:77], v[76:77], 1.0 op_sel_hi:[1,0]
	v_pk_add_f32 v[78:79], v[78:79], 1.0 op_sel_hi:[1,0]
	v_pk_add_f32 v[72:73], v[72:73], 1.0 op_sel_hi:[1,0]
	v_pk_add_f32 v[74:75], v[74:75], 1.0 op_sel_hi:[1,0]
	v_rcp_f32_e32 v76, v76
	v_rcp_f32_e32 v77, v77
	v_rcp_f32_e32 v78, v78
	v_rcp_f32_e32 v79, v79
	v_rcp_f32_e32 v72, v72
	v_rcp_f32_e32 v73, v73
	v_rcp_f32_e32 v74, v74
	v_rcp_f32_e32 v75, v75
	s_waitcnt vmcnt(13)
	v_lshlrev_b32_e32 v168, 16, v172
	v_and_b32_e32 v169, 0xffff0000, v172
	v_lshlrev_b32_e32 v188, 16, v180
	v_and_b32_e32 v189, 0xffff0000, v180
	v_pk_mul_f32 v[168:169], v[168:169], v[188:189]
	v_pk_mul_f32 v[116:117], v[168:169], v[116:117]
	v_lshlrev_b32_e32 v170, 16, v173
	v_and_b32_e32 v171, 0xffff0000, v173
	v_lshlrev_b32_e32 v190, 16, v181
	v_and_b32_e32 v191, 0xffff0000, v181
	v_pk_mul_f32 v[170:171], v[170:171], v[190:191]
	v_pk_mul_f32 v[118:119], v[170:171], v[118:119]
	v_lshlrev_b32_e32 v168, 16, v174
	v_and_b32_e32 v169, 0xffff0000, v174
	v_lshlrev_b32_e32 v188, 16, v182
	v_and_b32_e32 v189, 0xffff0000, v182
	v_pk_mul_f32 v[168:169], v[168:169], v[188:189]
	v_pk_mul_f32 v[112:113], v[168:169], v[112:113]
	v_lshlrev_b32_e32 v170, 16, v175
	v_and_b32_e32 v171, 0xffff0000, v175
	v_lshlrev_b32_e32 v190, 16, v183
	v_and_b32_e32 v191, 0xffff0000, v183
	v_pk_mul_f32 v[170:171], v[170:171], v[190:191]
	v_pk_mul_f32 v[114:115], v[170:171], v[114:115]
	global_load_dwordx4 v[180:183], v239, s[98:99] offset:256
	global_load_dwordx4 v[172:175], v185, s[10:11] offset:2048
	v_cvt_pk_bf16_f32 v116, v116, v117
	v_cvt_pk_bf16_f32 v117, v118, v119
	v_cvt_pk_bf16_f32 v118, v112, v113
	v_cvt_pk_bf16_f32 v119, v114, v115
	global_store_dwordx4 v239, v[116:119], s[100:101] offset:256
	v_cvt_f32_i32_e32 v52, v52
	v_cvt_f32_i32_e32 v53, v53
	v_cvt_f32_i32_e32 v54, v54
	v_cvt_f32_i32_e32 v55, v55
	v_cvt_f32_i32_e32 v48, v48
	v_cvt_f32_i32_e32 v49, v49
	v_cvt_f32_i32_e32 v50, v50
	v_cvt_f32_i32_e32 v51, v51
	v_pk_fma_f32 v[52:53], v[186:187], v[52:53], v[136:137] op_sel_hi:[0,1,1]
	v_pk_fma_f32 v[54:55], v[186:187], v[54:55], v[138:139] op_sel_hi:[0,1,1]
	v_pk_fma_f32 v[48:49], v[186:187], v[48:49], v[140:141] op_sel_hi:[0,1,1]
	v_pk_fma_f32 v[50:51], v[186:187], v[50:51], v[142:143] op_sel_hi:[0,1,1]
	v_pk_mul_f32 v[52:53], v[52:53], s[32:33] op_sel_hi:[1,0]
	v_pk_mul_f32 v[54:55], v[54:55], s[32:33] op_sel_hi:[1,0]
	v_pk_mul_f32 v[48:49], v[48:49], s[32:33] op_sel_hi:[1,0]
	v_pk_mul_f32 v[50:51], v[50:51], s[32:33] op_sel_hi:[1,0]
	v_exp_f32_e32 v52, v52
	v_exp_f32_e32 v53, v53
	v_exp_f32_e32 v54, v54
	v_exp_f32_e32 v55, v55
	v_exp_f32_e32 v48, v48
	v_exp_f32_e32 v49, v49
	v_exp_f32_e32 v50, v50
	v_exp_f32_e32 v51, v51
	v_pk_add_f32 v[52:53], v[52:53], 1.0 op_sel_hi:[1,0]
	v_pk_add_f32 v[54:55], v[54:55], 1.0 op_sel_hi:[1,0]
	v_pk_add_f32 v[48:49], v[48:49], 1.0 op_sel_hi:[1,0]
	v_pk_add_f32 v[50:51], v[50:51], 1.0 op_sel_hi:[1,0]
	v_rcp_f32_e32 v52, v52
	v_rcp_f32_e32 v53, v53
	v_rcp_f32_e32 v54, v54
	v_rcp_f32_e32 v55, v55
	v_rcp_f32_e32 v48, v48
	v_rcp_f32_e32 v49, v49
	v_rcp_f32_e32 v50, v50
	v_rcp_f32_e32 v51, v51
	s_waitcnt vmcnt(14)
; __device__ __forceinline__ unsigned cvt_pk_bf16(float lo, float hi) { unsigned r; asm volatile("v_cvt_pk_bf16_f32 %0, %1, %2" : "=v"(r) : "v"(lo), "v"(hi)); return r; }
; __device__ __forceinline__ float bf_lo(unsigned w) { return __uint_as_float(w << 16); }
; __device__ __forceinline__ float bf_hi(unsigned w) { return __uint_as_float(w & 0xffff0000u); }
; __device__ __forceinline__ float fast_sigmoid(float x) { return __builtin_amdgcn_rcpf(1.0f + __builtin_amdgcn_exp2f(-1.4426950408889634f * x)); }
;     __device__ __forceinline__ void operator()(const f32x4 (&acc)[2][2][4][2], const Unit& u, int wr, int wc, int fr, int fq) const {
;     ...
;                 for (int bj = 0; bj < 2; ++bj) { const u32x4 yv = *(const u32x4*)(YA + offy + (size_t)bj * 8 * SEQ * 16), zv = *(const u32x4*)(SZ + off + bj * HALF);
;                     const i32x4 q0 = __builtin_bit_cast(i32x4, acc[ai][bj][m][0]), q1 = __builtin_bit_cast(i32x4, acc[ai][bj][m][1]);
;                     const f32x4 g0 = (f32x4){(float)q0[0], (float)q0[1], (float)q0[2], (float)q0[3]} * GATE_DEQ + bv[bj][0], g1 = (f32x4){(float)q1[0], (float)q1[1], (float)q1[2], (float)q1[3]} * GATE_DEQ + bv[bj][1];
;                     float o[8];
;                     o[0] = bf_lo(yv.x) * bf_lo(zv.x) * fast_sigmoid(g0[0]); o[1] = bf_hi(yv.x) * bf_hi(zv.x) * fast_sigmoid(g0[1]);
;                     o[2] = bf_lo(yv.y) * bf_lo(zv.y) * fast_sigmoid(g0[2]); o[3] = bf_hi(yv.y) * bf_hi(zv.y) * fast_sigmoid(g0[3]);
;                     o[4] = bf_lo(yv.z) * bf_lo(zv.z) * fast_sigmoid(g1[0]); o[5] = bf_hi(yv.z) * bf_hi(zv.z) * fast_sigmoid(g1[1]);
;                     o[6] = bf_lo(yv.w) * bf_lo(zv.w) * fast_sigmoid(g1[2]); o[7] = bf_hi(yv.w) * bf_hi(zv.w) * fast_sigmoid(g1[3]);
;                     u32x4 w; w.x = cvt_pk_bf16(o[0], o[1]); w.y = cvt_pk_bf16(o[2], o[3]); w.z = cvt_pk_bf16(o[4], o[5]); w.w = cvt_pk_bf16(o[6], o[7]);
;                     *(u32x4*)(V + off + bj * HALF) = w; } }
	v_lshlrev_b32_e32 v168, 16, v240
	v_and_b32_e32 v169, 0xffff0000, v240
	v_lshlrev_b32_e32 v188, 16, v244
	v_and_b32_e32 v189, 0xffff0000, v244
	v_pk_mul_f32 v[168:169], v[168:169], v[188:189]
	v_pk_mul_f32 v[108:109], v[168:169], v[108:109]
	v_lshlrev_b32_e32 v170, 16, v241
	v_and_b32_e32 v171, 0xffff0000, v241
	v_lshlrev_b32_e32 v190, 16, v245
	v_and_b32_e32 v191, 0xffff0000, v245
	v_pk_mul_f32 v[170:171], v[170:171], v[190:191]
	v_pk_mul_f32 v[110:111], v[170:171], v[110:111]
	v_lshlrev_b32_e32 v168, 16, v242
	v_and_b32_e32 v169, 0xffff0000, v242
	v_lshlrev_b32_e32 v188, 16, v246
	v_and_b32_e32 v189, 0xffff0000, v246
	v_pk_mul_f32 v[168:169], v[168:169], v[188:189]
	v_pk_mul_f32 v[104:105], v[168:169], v[104:105]
	v_lshlrev_b32_e32 v170, 16, v243
	v_and_b32_e32 v171, 0xffff0000, v243
	v_lshlrev_b32_e32 v190, 16, v247
	v_and_b32_e32 v191, 0xffff0000, v247
	v_pk_mul_f32 v[170:171], v[170:171], v[190:191]
	v_pk_mul_f32 v[106:107], v[170:171], v[106:107]
	s_add_u32 s98, s12, 0x240000
	s_addc_u32 s99, s13, 0
	global_load_dwordx4 v[244:247], v239, s[98:99]
	global_load_dwordx4 v[240:243], v184, s[10:11] offset:2560
	v_cvt_pk_bf16_f32 v108, v108, v109
	v_cvt_pk_bf16_f32 v109, v110, v111
	v_cvt_pk_bf16_f32 v110, v104, v105
	v_cvt_pk_bf16_f32 v111, v106, v107
	s_add_u32 s100, s16, 0x80000
	s_addc_u32 s101, s17, 0
	global_store_dwordx4 v239, v[108:111], s[100:101]
	v_cvt_f32_i32_e32 v44, v44
	v_cvt_f32_i32_e32 v45, v45
	v_cvt_f32_i32_e32 v46, v46
	v_cvt_f32_i32_e32 v47, v47
	v_cvt_f32_i32_e32 v40, v40
	v_cvt_f32_i32_e32 v41, v41
	v_cvt_f32_i32_e32 v42, v42
	v_cvt_f32_i32_e32 v43, v43
	v_pk_fma_f32 v[44:45], v[186:187], v[44:45], v[68:69] op_sel_hi:[0,1,1]
	v_pk_fma_f32 v[46:47], v[186:187], v[46:47], v[70:71] op_sel_hi:[0,1,1]
	v_pk_fma_f32 v[40:41], v[186:187], v[40:41], v[64:65] op_sel_hi:[0,1,1]
	v_pk_fma_f32 v[42:43], v[186:187], v[42:43], v[66:67] op_sel_hi:[0,1,1]
	v_pk_mul_f32 v[44:45], v[44:45], s[32:33] op_sel_hi:[1,0]
	v_pk_mul_f32 v[46:47], v[46:47], s[32:33] op_sel_hi:[1,0]
	v_pk_mul_f32 v[40:41], v[40:41], s[32:33] op_sel_hi:[1,0]
	v_pk_mul_f32 v[42:43], v[42:43], s[32:33] op_sel_hi:[1,0]
	v_exp_f32_e32 v44, v44
	v_exp_f32_e32 v45, v45
	v_exp_f32_e32 v46, v46
	v_exp_f32_e32 v47, v47
	v_exp_f32_e32 v40, v40
	v_exp_f32_e32 v41, v41
	v_exp_f32_e32 v42, v42
	v_exp_f32_e32 v43, v43
	v_pk_add_f32 v[44:45], v[44:45], 1.0 op_sel_hi:[1,0]
	v_pk_add_f32 v[46:47], v[46:47], 1.0 op_sel_hi:[1,0]
	v_pk_add_f32 v[40:41], v[40:41], 1.0 op_sel_hi:[1,0]
	v_pk_add_f32 v[42:43], v[42:43], 1.0 op_sel_hi:[1,0]
	v_rcp_f32_e32 v44, v44
	v_rcp_f32_e32 v45, v45
	v_rcp_f32_e32 v46, v46
	v_rcp_f32_e32 v47, v47
	v_rcp_f32_e32 v40, v40
	v_rcp_f32_e32 v41, v41
	v_rcp_f32_e32 v42, v42
	v_rcp_f32_e32 v43, v43
	s_waitcnt vmcnt(15)
	v_lshlrev_b32_e32 v168, 16, v248
	v_and_b32_e32 v169, 0xffff0000, v248
	v_lshlrev_b32_e32 v188, 16, v176
	v_and_b32_e32 v189, 0xffff0000, v176
	v_pk_mul_f32 v[168:169], v[168:169], v[188:189]
	v_pk_mul_f32 v[100:101], v[168:169], v[100:101]
	v_lshlrev_b32_e32 v170, 16, v249
	v_and_b32_e32 v171, 0xffff0000, v249
	v_lshlrev_b32_e32 v190, 16, v177
	v_and_b32_e32 v191, 0xffff0000, v177
	v_pk_mul_f32 v[170:171], v[170:171], v[190:191]
	v_pk_mul_f32 v[102:103], v[170:171], v[102:103]
	v_lshlrev_b32_e32 v168, 16, v250
	v_and_b32_e32 v169, 0xffff0000, v250
	v_lshlrev_b32_e32 v188, 16, v178
	v_and_b32_e32 v189, 0xffff0000, v178
	v_pk_mul_f32 v[168:169], v[168:169], v[188:189]
	v_pk_mul_f32 v[96:97], v[168:169], v[96:97]
	v_lshlrev_b32_e32 v170, 16, v251
	v_and_b32_e32 v171, 0xffff0000, v251
	v_lshlrev_b32_e32 v190, 16, v179
	v_and_b32_e32 v191, 0xffff0000, v179
	v_pk_mul_f32 v[170:171], v[170:171], v[190:191]
	v_pk_mul_f32 v[98:99], v[170:171], v[98:99]
	global_load_dwordx4 v[176:179], v239, s[98:99] offset:256
	global_load_dwordx4 v[248:251], v185, s[10:11] offset:2560
	v_cvt_pk_bf16_f32 v100, v100, v101
	v_cvt_pk_bf16_f32 v101, v102, v103
	v_cvt_pk_bf16_f32 v102, v96, v97
	v_cvt_pk_bf16_f32 v103, v98, v99
	global_store_dwordx4 v239, v[100:103], s[100:101] offset:256
	v_cvt_f32_i32_e32 v36, v36
	v_cvt_f32_i32_e32 v37, v37
	v_cvt_f32_i32_e32 v38, v38
	v_cvt_f32_i32_e32 v39, v39
	v_cvt_f32_i32_e32 v32, v32
	v_cvt_f32_i32_e32 v33, v33
	v_cvt_f32_i32_e32 v34, v34
	v_cvt_f32_i32_e32 v35, v35
	v_pk_fma_f32 v[36:37], v[186:187], v[36:37], v[136:137] op_sel_hi:[0,1,1]
	v_pk_fma_f32 v[38:39], v[186:187], v[38:39], v[138:139] op_sel_hi:[0,1,1]
	v_pk_fma_f32 v[32:33], v[186:187], v[32:33], v[140:141] op_sel_hi:[0,1,1]
	v_pk_fma_f32 v[34:35], v[186:187], v[34:35], v[142:143] op_sel_hi:[0,1,1]
	v_pk_mul_f32 v[36:37], v[36:37], s[32:33] op_sel_hi:[1,0]
	v_pk_mul_f32 v[38:39], v[38:39], s[32:33] op_sel_hi:[1,0]
	v_pk_mul_f32 v[32:33], v[32:33], s[32:33] op_sel_hi:[1,0]
	v_pk_mul_f32 v[34:35], v[34:35], s[32:33] op_sel_hi:[1,0]
	v_exp_f32_e32 v36, v36
	v_exp_f32_e32 v37, v37
	v_exp_f32_e32 v38, v38
	v_exp_f32_e32 v39, v39
	v_exp_f32_e32 v32, v32
	v_exp_f32_e32 v33, v33
	v_exp_f32_e32 v34, v34
	v_exp_f32_e32 v35, v35
	v_pk_add_f32 v[36:37], v[36:37], 1.0 op_sel_hi:[1,0]
	v_pk_add_f32 v[38:39], v[38:39], 1.0 op_sel_hi:[1,0]
	v_pk_add_f32 v[32:33], v[32:33], 1.0 op_sel_hi:[1,0]
	v_pk_add_f32 v[34:35], v[34:35], 1.0 op_sel_hi:[1,0]
	v_rcp_f32_e32 v36, v36
	v_rcp_f32_e32 v37, v37
	v_rcp_f32_e32 v38, v38
	v_rcp_f32_e32 v39, v39
	v_rcp_f32_e32 v32, v32
	v_rcp_f32_e32 v33, v33
	v_rcp_f32_e32 v34, v34
	v_rcp_f32_e32 v35, v35
	s_waitcnt vmcnt(16)
; __device__ __forceinline__ unsigned cvt_pk_bf16(float lo, float hi) { unsigned r; asm volatile("v_cvt_pk_bf16_f32 %0, %1, %2" : "=v"(r) : "v"(lo), "v"(hi)); return r; }
; __device__ __forceinline__ float bf_lo(unsigned w) { return __uint_as_float(w << 16); }
; __device__ __forceinline__ float bf_hi(unsigned w) { return __uint_as_float(w & 0xffff0000u); }
; __device__ __forceinline__ float fast_sigmoid(float x) { return __builtin_amdgcn_rcpf(1.0f + __builtin_amdgcn_exp2f(-1.4426950408889634f * x)); }
;     __device__ __forceinline__ void operator()(const f32x4 (&acc)[2][2][4][2], const Unit& u, int wr, int wc, int fr, int fq) const {
;     ...
;                 for (int bj = 0; bj < 2; ++bj) { const u32x4 yv = *(const u32x4*)(YA + offy + (size_t)bj * 8 * SEQ * 16), zv = *(const u32x4*)(SZ + off + bj * HALF);
;                     const i32x4 q0 = __builtin_bit_cast(i32x4, acc[ai][bj][m][0]), q1 = __builtin_bit_cast(i32x4, acc[ai][bj][m][1]);
;                     const f32x4 g0 = (f32x4){(float)q0[0], (float)q0[1], (float)q0[2], (float)q0[3]} * GATE_DEQ + bv[bj][0], g1 = (f32x4){(float)q1[0], (float)q1[1], (float)q1[2], (float)q1[3]} * GATE_DEQ + bv[bj][1];
;                     float o[8];
;                     o[0] = bf_lo(yv.x) * bf_lo(zv.x) * fast_sigmoid(g0[0]); o[1] = bf_hi(yv.x) * bf_hi(zv.x) * fast_sigmoid(g0[1]);
;                     o[2] = bf_lo(yv.y) * bf_lo(zv.y) * fast_sigmoid(g0[2]); o[3] = bf_hi(yv.y) * bf_hi(zv.y) * fast_sigmoid(g0[3]);
;                     o[4] = bf_lo(yv.z) * bf_lo(zv.z) * fast_sigmoid(g1[0]); o[5] = bf_hi(yv.z) * bf_hi(zv.z) * fast_sigmoid(g1[1]);
;                     o[6] = bf_lo(yv.w) * bf_lo(zv.w) * fast_sigmoid(g1[2]); o[7] = bf_hi(yv.w) * bf_hi(zv.w) * fast_sigmoid(g1[3]);
;                     u32x4 w; w.x = cvt_pk_bf16(o[0], o[1]); w.y = cvt_pk_bf16(o[2], o[3]); w.z = cvt_pk_bf16(o[4], o[5]); w.w = cvt_pk_bf16(o[6], o[7]);
;                     *(u32x4*)(V + off + bj * HALF) = w; } }
	v_lshlrev_b32_e32 v168, 16, v144
	v_and_b32_e32 v169, 0xffff0000, v144
	v_lshlrev_b32_e32 v188, 16, v148
	v_and_b32_e32 v189, 0xffff0000, v148
	v_pk_mul_f32 v[168:169], v[168:169], v[188:189]
	v_pk_mul_f32 v[92:93], v[168:169], v[92:93]
	v_lshlrev_b32_e32 v170, 16, v145
	v_and_b32_e32 v171, 0xffff0000, v145
	v_lshlrev_b32_e32 v190, 16, v149
	v_and_b32_e32 v191, 0xffff0000, v149
	v_pk_mul_f32 v[170:171], v[170:171], v[190:191]
	v_pk_mul_f32 v[94:95], v[170:171], v[94:95]
	v_lshlrev_b32_e32 v168, 16, v146
	v_and_b32_e32 v169, 0xffff0000, v146
	v_lshlrev_b32_e32 v188, 16, v150
	v_and_b32_e32 v189, 0xffff0000, v150
	v_pk_mul_f32 v[168:169], v[168:169], v[188:189]
	v_pk_mul_f32 v[88:89], v[168:169], v[88:89]
	v_lshlrev_b32_e32 v170, 16, v147
	v_and_b32_e32 v171, 0xffff0000, v147
	v_lshlrev_b32_e32 v190, 16, v151
	v_and_b32_e32 v191, 0xffff0000, v151
	v_pk_mul_f32 v[170:171], v[170:171], v[190:191]
	v_pk_mul_f32 v[90:91], v[170:171], v[90:91]
	s_add_u32 s98, s12, 0x280000
	s_addc_u32 s99, s13, 0
	global_load_dwordx4 v[148:151], v239, s[98:99]
	global_load_dwordx4 v[144:147], v184, s[10:11] offset:3072
	v_cvt_pk_bf16_f32 v92, v92, v93
	v_cvt_pk_bf16_f32 v93, v94, v95
	v_cvt_pk_bf16_f32 v94, v88, v89
	v_cvt_pk_bf16_f32 v95, v90, v91
	s_add_u32 s100, s16, 0xc0000
	s_addc_u32 s101, s17, 0
	global_store_dwordx4 v239, v[92:95], s[100:101]
	v_cvt_f32_i32_e32 v28, v28
	v_cvt_f32_i32_e32 v29, v29
	v_cvt_f32_i32_e32 v30, v30
	v_cvt_f32_i32_e32 v31, v31
	v_cvt_f32_i32_e32 v24, v24
	v_cvt_f32_i32_e32 v25, v25
	v_cvt_f32_i32_e32 v26, v26
	v_cvt_f32_i32_e32 v27, v27
	v_pk_fma_f32 v[28:29], v[186:187], v[28:29], v[68:69] op_sel_hi:[0,1,1]
	v_pk_fma_f32 v[30:31], v[186:187], v[30:31], v[70:71] op_sel_hi:[0,1,1]
	v_pk_fma_f32 v[24:25], v[186:187], v[24:25], v[64:65] op_sel_hi:[0,1,1]
	v_pk_fma_f32 v[26:27], v[186:187], v[26:27], v[66:67] op_sel_hi:[0,1,1]
	v_pk_mul_f32 v[28:29], v[28:29], s[32:33] op_sel_hi:[1,0]
	v_pk_mul_f32 v[30:31], v[30:31], s[32:33] op_sel_hi:[1,0]
	v_pk_mul_f32 v[24:25], v[24:25], s[32:33] op_sel_hi:[1,0]
	v_pk_mul_f32 v[26:27], v[26:27], s[32:33] op_sel_hi:[1,0]
	v_exp_f32_e32 v28, v28
	v_exp_f32_e32 v29, v29
	v_exp_f32_e32 v30, v30
	v_exp_f32_e32 v31, v31
	v_exp_f32_e32 v24, v24
	v_exp_f32_e32 v25, v25
	v_exp_f32_e32 v26, v26
	v_exp_f32_e32 v27, v27
	v_pk_add_f32 v[28:29], v[28:29], 1.0 op_sel_hi:[1,0]
	v_pk_add_f32 v[30:31], v[30:31], 1.0 op_sel_hi:[1,0]
	v_pk_add_f32 v[24:25], v[24:25], 1.0 op_sel_hi:[1,0]
	v_pk_add_f32 v[26:27], v[26:27], 1.0 op_sel_hi:[1,0]
	v_rcp_f32_e32 v28, v28
	v_rcp_f32_e32 v29, v29
	v_rcp_f32_e32 v30, v30
	v_rcp_f32_e32 v31, v31
	v_rcp_f32_e32 v24, v24
	v_rcp_f32_e32 v25, v25
	v_rcp_f32_e32 v26, v26
	v_rcp_f32_e32 v27, v27
	s_waitcnt vmcnt(16)
	v_lshlrev_b32_e32 v168, 16, v152
	v_and_b32_e32 v169, 0xffff0000, v152
	v_lshlrev_b32_e32 v188, 16, v156
	v_and_b32_e32 v189, 0xffff0000, v156
	v_pk_mul_f32 v[168:169], v[168:169], v[188:189]
	v_pk_mul_f32 v[84:85], v[168:169], v[84:85]
	v_lshlrev_b32_e32 v170, 16, v153
	v_and_b32_e32 v171, 0xffff0000, v153
	v_lshlrev_b32_e32 v190, 16, v157
	v_and_b32_e32 v191, 0xffff0000, v157
	v_pk_mul_f32 v[170:171], v[170:171], v[190:191]
	v_pk_mul_f32 v[86:87], v[170:171], v[86:87]
	v_lshlrev_b32_e32 v168, 16, v154
	v_and_b32_e32 v169, 0xffff0000, v154
	v_lshlrev_b32_e32 v188, 16, v158
	v_and_b32_e32 v189, 0xffff0000, v158
	v_pk_mul_f32 v[168:169], v[168:169], v[188:189]
	v_pk_mul_f32 v[80:81], v[168:169], v[80:81]
	v_lshlrev_b32_e32 v170, 16, v155
	v_and_b32_e32 v171, 0xffff0000, v155
	v_lshlrev_b32_e32 v190, 16, v159
	v_and_b32_e32 v191, 0xffff0000, v159
	v_pk_mul_f32 v[170:171], v[170:171], v[190:191]
	v_pk_mul_f32 v[82:83], v[170:171], v[82:83]
	global_load_dwordx4 v[156:159], v239, s[98:99] offset:256
	global_load_dwordx4 v[152:155], v185, s[10:11] offset:3072
	v_cvt_pk_bf16_f32 v84, v84, v85
	v_cvt_pk_bf16_f32 v85, v86, v87
	v_cvt_pk_bf16_f32 v86, v80, v81
	v_cvt_pk_bf16_f32 v87, v82, v83
	global_store_dwordx4 v239, v[84:87], s[100:101] offset:256
	v_cvt_f32_i32_e32 v20, v20
	v_cvt_f32_i32_e32 v21, v21
	v_cvt_f32_i32_e32 v22, v22
	v_cvt_f32_i32_e32 v23, v23
	v_cvt_f32_i32_e32 v16, v16
	v_cvt_f32_i32_e32 v17, v17
	v_cvt_f32_i32_e32 v18, v18
	v_cvt_f32_i32_e32 v19, v19
	v_pk_fma_f32 v[20:21], v[186:187], v[20:21], v[136:137] op_sel_hi:[0,1,1]
	v_pk_fma_f32 v[22:23], v[186:187], v[22:23], v[138:139] op_sel_hi:[0,1,1]
	v_pk_fma_f32 v[16:17], v[186:187], v[16:17], v[140:141] op_sel_hi:[0,1,1]
	v_pk_fma_f32 v[18:19], v[186:187], v[18:19], v[142:143] op_sel_hi:[0,1,1]
	v_pk_mul_f32 v[20:21], v[20:21], s[32:33] op_sel_hi:[1,0]
	v_pk_mul_f32 v[22:23], v[22:23], s[32:33] op_sel_hi:[1,0]
	v_pk_mul_f32 v[16:17], v[16:17], s[32:33] op_sel_hi:[1,0]
	v_pk_mul_f32 v[18:19], v[18:19], s[32:33] op_sel_hi:[1,0]
	v_exp_f32_e32 v20, v20
	v_exp_f32_e32 v21, v21
	v_exp_f32_e32 v22, v22
	v_exp_f32_e32 v23, v23
	v_exp_f32_e32 v16, v16
	v_exp_f32_e32 v17, v17
	v_exp_f32_e32 v18, v18
	v_exp_f32_e32 v19, v19
	v_pk_add_f32 v[20:21], v[20:21], 1.0 op_sel_hi:[1,0]
	v_pk_add_f32 v[22:23], v[22:23], 1.0 op_sel_hi:[1,0]
	v_pk_add_f32 v[16:17], v[16:17], 1.0 op_sel_hi:[1,0]
	v_pk_add_f32 v[18:19], v[18:19], 1.0 op_sel_hi:[1,0]
	v_rcp_f32_e32 v20, v20
	v_rcp_f32_e32 v21, v21
	v_rcp_f32_e32 v22, v22
	v_rcp_f32_e32 v23, v23
	v_rcp_f32_e32 v16, v16
	v_rcp_f32_e32 v17, v17
	v_rcp_f32_e32 v18, v18
	v_rcp_f32_e32 v19, v19
	s_waitcnt vmcnt(16)
; __device__ __forceinline__ unsigned cvt_pk_bf16(float lo, float hi) { unsigned r; asm volatile("v_cvt_pk_bf16_f32 %0, %1, %2" : "=v"(r) : "v"(lo), "v"(hi)); return r; }
; __device__ __forceinline__ float bf_lo(unsigned w) { return __uint_as_float(w << 16); }
; __device__ __forceinline__ float bf_hi(unsigned w) { return __uint_as_float(w & 0xffff0000u); }
; __device__ __forceinline__ float fast_sigmoid(float x) { return __builtin_amdgcn_rcpf(1.0f + __builtin_amdgcn_exp2f(-1.4426950408889634f * x)); }
;     __device__ __forceinline__ void operator()(const f32x4 (&acc)[2][2][4][2], const Unit& u, int wr, int wc, int fr, int fq) const {
;     ...
;                 for (int bj = 0; bj < 2; ++bj) { const u32x4 yv = *(const u32x4*)(YA + offy + (size_t)bj * 8 * SEQ * 16), zv = *(const u32x4*)(SZ + off + bj * HALF);
;                     const i32x4 q0 = __builtin_bit_cast(i32x4, acc[ai][bj][m][0]), q1 = __builtin_bit_cast(i32x4, acc[ai][bj][m][1]);
;                     const f32x4 g0 = (f32x4){(float)q0[0], (float)q0[1], (float)q0[2], (float)q0[3]} * GATE_DEQ + bv[bj][0], g1 = (f32x4){(float)q1[0], (float)q1[1], (float)q1[2], (float)q1[3]} * GATE_DEQ + bv[bj][1];
;                     float o[8];
;                     o[0] = bf_lo(yv.x) * bf_lo(zv.x) * fast_sigmoid(g0[0]); o[1] = bf_hi(yv.x) * bf_hi(zv.x) * fast_sigmoid(g0[1]);
;                     o[2] = bf_lo(yv.y) * bf_lo(zv.y) * fast_sigmoid(g0[2]); o[3] = bf_hi(yv.y) * bf_hi(zv.y) * fast_sigmoid(g0[3]);
;                     o[4] = bf_lo(yv.z) * bf_lo(zv.z) * fast_sigmoid(g1[0]); o[5] = bf_hi(yv.z) * bf_hi(zv.z) * fast_sigmoid(g1[1]);
;                     o[6] = bf_lo(yv.w) * bf_lo(zv.w) * fast_sigmoid(g1[2]); o[7] = bf_hi(yv.w) * bf_hi(zv.w) * fast_sigmoid(g1[3]);
;                     u32x4 w; w.x = cvt_pk_bf16(o[0], o[1]); w.y = cvt_pk_bf16(o[2], o[3]); w.z = cvt_pk_bf16(o[4], o[5]); w.w = cvt_pk_bf16(o[6], o[7]);
;                     *(u32x4*)(V + off + bj * HALF) = w; } }
	v_lshlrev_b32_e32 v168, 16, v160
	v_and_b32_e32 v169, 0xffff0000, v160
	v_lshlrev_b32_e32 v188, 16, v164
	v_and_b32_e32 v189, 0xffff0000, v164
	v_pk_mul_f32 v[168:169], v[168:169], v[188:189]
	v_pk_mul_f32 v[76:77], v[168:169], v[76:77]
	v_lshlrev_b32_e32 v170, 16, v161
	v_and_b32_e32 v171, 0xffff0000, v161
	v_lshlrev_b32_e32 v190, 16, v165
	v_and_b32_e32 v191, 0xffff0000, v165
	v_pk_mul_f32 v[170:171], v[170:171], v[190:191]
	v_pk_mul_f32 v[78:79], v[170:171], v[78:79]
	v_lshlrev_b32_e32 v168, 16, v162
	v_and_b32_e32 v169, 0xffff0000, v162
	v_lshlrev_b32_e32 v188, 16, v166
	v_and_b32_e32 v189, 0xffff0000, v166
	v_pk_mul_f32 v[168:169], v[168:169], v[188:189]
	v_pk_mul_f32 v[72:73], v[168:169], v[72:73]
	v_lshlrev_b32_e32 v170, 16, v163
	v_and_b32_e32 v171, 0xffff0000, v163
	v_lshlrev_b32_e32 v190, 16, v167
	v_and_b32_e32 v191, 0xffff0000, v167
	v_pk_mul_f32 v[170:171], v[170:171], v[190:191]
	v_pk_mul_f32 v[74:75], v[170:171], v[74:75]
	s_add_u32 s98, s12, 0x2c0000
	s_addc_u32 s99, s13, 0
	global_load_dwordx4 v[164:167], v239, s[98:99]
	global_load_dwordx4 v[160:163], v184, s[10:11] offset:3584
	v_cvt_pk_bf16_f32 v76, v76, v77
	v_cvt_pk_bf16_f32 v77, v78, v79
	v_cvt_pk_bf16_f32 v78, v72, v73
	v_cvt_pk_bf16_f32 v79, v74, v75
	s_add_u32 s100, s16, 0x200000
	s_addc_u32 s101, s17, 0
	global_store_dwordx4 v239, v[76:79], s[100:101]
	v_cvt_f32_i32_e32 v12, v12
	v_cvt_f32_i32_e32 v13, v13
	v_cvt_f32_i32_e32 v14, v14
	v_cvt_f32_i32_e32 v15, v15
	v_cvt_f32_i32_e32 v8, v8
	v_cvt_f32_i32_e32 v9, v9
	v_cvt_f32_i32_e32 v10, v10
	v_cvt_f32_i32_e32 v11, v11
	v_pk_fma_f32 v[12:13], v[186:187], v[12:13], v[68:69] op_sel_hi:[0,1,1]
	v_pk_fma_f32 v[14:15], v[186:187], v[14:15], v[70:71] op_sel_hi:[0,1,1]
	v_pk_fma_f32 v[8:9], v[186:187], v[8:9], v[64:65] op_sel_hi:[0,1,1]
	v_pk_fma_f32 v[10:11], v[186:187], v[10:11], v[66:67] op_sel_hi:[0,1,1]
	v_pk_mul_f32 v[12:13], v[12:13], s[32:33] op_sel_hi:[1,0]
	v_pk_mul_f32 v[14:15], v[14:15], s[32:33] op_sel_hi:[1,0]
	v_pk_mul_f32 v[8:9], v[8:9], s[32:33] op_sel_hi:[1,0]
	v_pk_mul_f32 v[10:11], v[10:11], s[32:33] op_sel_hi:[1,0]
	v_exp_f32_e32 v12, v12
	v_exp_f32_e32 v13, v13
	v_exp_f32_e32 v14, v14
	v_exp_f32_e32 v15, v15
	v_exp_f32_e32 v8, v8
	v_exp_f32_e32 v9, v9
	v_exp_f32_e32 v10, v10
	v_exp_f32_e32 v11, v11
	v_pk_add_f32 v[12:13], v[12:13], 1.0 op_sel_hi:[1,0]
	v_pk_add_f32 v[14:15], v[14:15], 1.0 op_sel_hi:[1,0]
	v_pk_add_f32 v[8:9], v[8:9], 1.0 op_sel_hi:[1,0]
	v_pk_add_f32 v[10:11], v[10:11], 1.0 op_sel_hi:[1,0]
	v_rcp_f32_e32 v12, v12
	v_rcp_f32_e32 v13, v13
	v_rcp_f32_e32 v14, v14
	v_rcp_f32_e32 v15, v15
	v_rcp_f32_e32 v8, v8
	v_rcp_f32_e32 v9, v9
	v_rcp_f32_e32 v10, v10
	v_rcp_f32_e32 v11, v11
	s_waitcnt vmcnt(16)
	v_lshlrev_b32_e32 v168, 16, v172
	v_and_b32_e32 v169, 0xffff0000, v172
	v_lshlrev_b32_e32 v188, 16, v180
	v_and_b32_e32 v189, 0xffff0000, v180
	v_pk_mul_f32 v[168:169], v[168:169], v[188:189]
	v_pk_mul_f32 v[52:53], v[168:169], v[52:53]
	v_lshlrev_b32_e32 v170, 16, v173
	v_and_b32_e32 v171, 0xffff0000, v173
	v_lshlrev_b32_e32 v190, 16, v181
	v_and_b32_e32 v191, 0xffff0000, v181
	v_pk_mul_f32 v[170:171], v[170:171], v[190:191]
	v_pk_mul_f32 v[54:55], v[170:171], v[54:55]
	v_lshlrev_b32_e32 v168, 16, v174
	v_and_b32_e32 v169, 0xffff0000, v174
	v_lshlrev_b32_e32 v188, 16, v182
	v_and_b32_e32 v189, 0xffff0000, v182
	v_pk_mul_f32 v[168:169], v[168:169], v[188:189]
	v_pk_mul_f32 v[48:49], v[168:169], v[48:49]
	v_lshlrev_b32_e32 v170, 16, v175
	v_and_b32_e32 v171, 0xffff0000, v175
	v_lshlrev_b32_e32 v190, 16, v183
	v_and_b32_e32 v191, 0xffff0000, v183
	v_pk_mul_f32 v[170:171], v[170:171], v[190:191]
	v_pk_mul_f32 v[50:51], v[170:171], v[50:51]
	global_load_dwordx4 v[180:183], v239, s[98:99] offset:256
	global_load_dwordx4 v[172:175], v185, s[10:11] offset:3584
	v_cvt_pk_bf16_f32 v52, v52, v53
	v_cvt_pk_bf16_f32 v53, v54, v55
	v_cvt_pk_bf16_f32 v54, v48, v49
	v_cvt_pk_bf16_f32 v55, v50, v51
	global_store_dwordx4 v239, v[52:55], s[100:101] offset:256
	v_cvt_f32_i32_e32 v4, v4
	v_cvt_f32_i32_e32 v5, v5
	v_cvt_f32_i32_e32 v6, v6
	v_cvt_f32_i32_e32 v7, v7
	v_cvt_f32_i32_e32 v0, v0
	v_cvt_f32_i32_e32 v1, v1
	v_cvt_f32_i32_e32 v2, v2
	v_cvt_f32_i32_e32 v3, v3
	v_pk_fma_f32 v[4:5], v[186:187], v[4:5], v[136:137] op_sel_hi:[0,1,1]
	v_pk_fma_f32 v[6:7], v[186:187], v[6:7], v[138:139] op_sel_hi:[0,1,1]
	v_pk_fma_f32 v[0:1], v[186:187], v[0:1], v[140:141] op_sel_hi:[0,1,1]
	v_pk_fma_f32 v[2:3], v[186:187], v[2:3], v[142:143] op_sel_hi:[0,1,1]
	v_pk_mul_f32 v[4:5], v[4:5], s[32:33] op_sel_hi:[1,0]
	v_pk_mul_f32 v[6:7], v[6:7], s[32:33] op_sel_hi:[1,0]
	v_pk_mul_f32 v[0:1], v[0:1], s[32:33] op_sel_hi:[1,0]
	v_pk_mul_f32 v[2:3], v[2:3], s[32:33] op_sel_hi:[1,0]
	v_exp_f32_e32 v4, v4
	v_exp_f32_e32 v5, v5
	v_exp_f32_e32 v6, v6
	v_exp_f32_e32 v7, v7
	v_exp_f32_e32 v0, v0
	v_exp_f32_e32 v1, v1
	v_exp_f32_e32 v2, v2
	v_exp_f32_e32 v3, v3
	v_pk_add_f32 v[4:5], v[4:5], 1.0 op_sel_hi:[1,0]
	v_pk_add_f32 v[6:7], v[6:7], 1.0 op_sel_hi:[1,0]
	v_pk_add_f32 v[0:1], v[0:1], 1.0 op_sel_hi:[1,0]
	v_pk_add_f32 v[2:3], v[2:3], 1.0 op_sel_hi:[1,0]
	v_rcp_f32_e32 v4, v4
	v_rcp_f32_e32 v5, v5
	v_rcp_f32_e32 v6, v6
	v_rcp_f32_e32 v7, v7
	v_rcp_f32_e32 v0, v0
	v_rcp_f32_e32 v1, v1
	v_rcp_f32_e32 v2, v2
	v_rcp_f32_e32 v3, v3
	s_waitcnt vmcnt(16)
; __device__ __forceinline__ unsigned cvt_pk_bf16(float lo, float hi) { unsigned r; asm volatile("v_cvt_pk_bf16_f32 %0, %1, %2" : "=v"(r) : "v"(lo), "v"(hi)); return r; }
; __device__ __forceinline__ float bf_lo(unsigned w) { return __uint_as_float(w << 16); }
; __device__ __forceinline__ float bf_hi(unsigned w) { return __uint_as_float(w & 0xffff0000u); }
; __device__ __forceinline__ float fast_sigmoid(float x) { return __builtin_amdgcn_rcpf(1.0f + __builtin_amdgcn_exp2f(-1.4426950408889634f * x)); }
;     __device__ __forceinline__ void operator()(const f32x4 (&acc)[2][2][4][2], const Unit& u, int wr, int wc, int fr, int fq) const {
;     ...
;                 for (int bj = 0; bj < 2; ++bj) { const u32x4 yv = *(const u32x4*)(YA + offy + (size_t)bj * 8 * SEQ * 16), zv = *(const u32x4*)(SZ + off + bj * HALF);
;                     const i32x4 q0 = __builtin_bit_cast(i32x4, acc[ai][bj][m][0]), q1 = __builtin_bit_cast(i32x4, acc[ai][bj][m][1]);
;                     const f32x4 g0 = (f32x4){(float)q0[0], (float)q0[1], (float)q0[2], (float)q0[3]} * GATE_DEQ + bv[bj][0], g1 = (f32x4){(float)q1[0], (float)q1[1], (float)q1[2], (float)q1[3]} * GATE_DEQ + bv[bj][1];
;                     float o[8];
;                     o[0] = bf_lo(yv.x) * bf_lo(zv.x) * fast_sigmoid(g0[0]); o[1] = bf_hi(yv.x) * bf_hi(zv.x) * fast_sigmoid(g0[1]);
;                     o[2] = bf_lo(yv.y) * bf_lo(zv.y) * fast_sigmoid(g0[2]); o[3] = bf_hi(yv.y) * bf_hi(zv.y) * fast_sigmoid(g0[3]);
;                     o[4] = bf_lo(yv.z) * bf_lo(zv.z) * fast_sigmoid(g1[0]); o[5] = bf_hi(yv.z) * bf_hi(zv.z) * fast_sigmoid(g1[1]);
;                     o[6] = bf_lo(yv.w) * bf_lo(zv.w) * fast_sigmoid(g1[2]); o[7] = bf_hi(yv.w) * bf_hi(zv.w) * fast_sigmoid(g1[3]);
;                     u32x4 w; w.x = cvt_pk_bf16(o[0], o[1]); w.y = cvt_pk_bf16(o[2], o[3]); w.z = cvt_pk_bf16(o[4], o[5]); w.w = cvt_pk_bf16(o[6], o[7]);
;                     *(u32x4*)(V + off + bj * HALF) = w; } }
	v_lshlrev_b32_e32 v168, 16, v240
	v_and_b32_e32 v169, 0xffff0000, v240
	v_lshlrev_b32_e32 v188, 16, v244
	v_and_b32_e32 v189, 0xffff0000, v244
	v_pk_mul_f32 v[168:169], v[168:169], v[188:189]
	v_pk_mul_f32 v[44:45], v[168:169], v[44:45]
	v_lshlrev_b32_e32 v170, 16, v241
	v_and_b32_e32 v171, 0xffff0000, v241
	v_lshlrev_b32_e32 v190, 16, v245
	v_and_b32_e32 v191, 0xffff0000, v245
	v_pk_mul_f32 v[170:171], v[170:171], v[190:191]
	v_pk_mul_f32 v[46:47], v[170:171], v[46:47]
	v_lshlrev_b32_e32 v168, 16, v242
	v_and_b32_e32 v169, 0xffff0000, v242
	v_lshlrev_b32_e32 v188, 16, v246
	v_and_b32_e32 v189, 0xffff0000, v246
	v_pk_mul_f32 v[168:169], v[168:169], v[188:189]
	v_pk_mul_f32 v[40:41], v[168:169], v[40:41]
	v_lshlrev_b32_e32 v170, 16, v243
	v_and_b32_e32 v171, 0xffff0000, v243
	v_lshlrev_b32_e32 v190, 16, v247
	v_and_b32_e32 v191, 0xffff0000, v247
	v_pk_mul_f32 v[170:171], v[170:171], v[190:191]
	v_pk_mul_f32 v[42:43], v[170:171], v[42:43]
	v_cvt_pk_bf16_f32 v44, v44, v45
	v_cvt_pk_bf16_f32 v45, v46, v47
	v_cvt_pk_bf16_f32 v46, v40, v41
	v_cvt_pk_bf16_f32 v47, v42, v43
	s_add_u32 s100, s16, 0x240000
	s_addc_u32 s101, s17, 0
	global_store_dwordx4 v239, v[44:47], s[100:101]
	s_waitcnt vmcnt(14)
	v_lshlrev_b32_e32 v168, 16, v248
	v_and_b32_e32 v169, 0xffff0000, v248
	v_lshlrev_b32_e32 v188, 16, v176
	v_and_b32_e32 v189, 0xffff0000, v176
	v_pk_mul_f32 v[168:169], v[168:169], v[188:189]
	v_pk_mul_f32 v[36:37], v[168:169], v[36:37]
	v_lshlrev_b32_e32 v170, 16, v249
	v_and_b32_e32 v171, 0xffff0000, v249
	v_lshlrev_b32_e32 v190, 16, v177
	v_and_b32_e32 v191, 0xffff0000, v177
	v_pk_mul_f32 v[170:171], v[170:171], v[190:191]
	v_pk_mul_f32 v[38:39], v[170:171], v[38:39]
	v_lshlrev_b32_e32 v168, 16, v250
	v_and_b32_e32 v169, 0xffff0000, v250
	v_lshlrev_b32_e32 v188, 16, v178
	v_and_b32_e32 v189, 0xffff0000, v178
	v_pk_mul_f32 v[168:169], v[168:169], v[188:189]
	v_pk_mul_f32 v[32:33], v[168:169], v[32:33]
	v_lshlrev_b32_e32 v170, 16, v251
	v_and_b32_e32 v171, 0xffff0000, v251
	v_lshlrev_b32_e32 v190, 16, v179
	v_and_b32_e32 v191, 0xffff0000, v179
	v_pk_mul_f32 v[170:171], v[170:171], v[190:191]
	v_pk_mul_f32 v[34:35], v[170:171], v[34:35]
	v_cvt_pk_bf16_f32 v36, v36, v37
	v_cvt_pk_bf16_f32 v37, v38, v39
	v_cvt_pk_bf16_f32 v38, v32, v33
	v_cvt_pk_bf16_f32 v39, v34, v35
	global_store_dwordx4 v239, v[36:39], s[100:101] offset:256
	s_waitcnt vmcnt(12)
	v_lshlrev_b32_e32 v168, 16, v144
	v_and_b32_e32 v169, 0xffff0000, v144
	v_lshlrev_b32_e32 v188, 16, v148
	v_and_b32_e32 v189, 0xffff0000, v148
	v_pk_mul_f32 v[168:169], v[168:169], v[188:189]
	v_pk_mul_f32 v[28:29], v[168:169], v[28:29]
	v_lshlrev_b32_e32 v170, 16, v145
	v_and_b32_e32 v171, 0xffff0000, v145
	v_lshlrev_b32_e32 v190, 16, v149
	v_and_b32_e32 v191, 0xffff0000, v149
	v_pk_mul_f32 v[170:171], v[170:171], v[190:191]
	v_pk_mul_f32 v[30:31], v[170:171], v[30:31]
	v_lshlrev_b32_e32 v168, 16, v146
	v_and_b32_e32 v169, 0xffff0000, v146
	v_lshlrev_b32_e32 v188, 16, v150
	v_and_b32_e32 v189, 0xffff0000, v150
	v_pk_mul_f32 v[168:169], v[168:169], v[188:189]
	v_pk_mul_f32 v[24:25], v[168:169], v[24:25]
	v_lshlrev_b32_e32 v170, 16, v147
	v_and_b32_e32 v171, 0xffff0000, v147
	v_lshlrev_b32_e32 v190, 16, v151
	v_and_b32_e32 v191, 0xffff0000, v151
	v_pk_mul_f32 v[170:171], v[170:171], v[190:191]
	v_pk_mul_f32 v[26:27], v[170:171], v[26:27]
	v_cvt_pk_bf16_f32 v28, v28, v29
	v_cvt_pk_bf16_f32 v29, v30, v31
	v_cvt_pk_bf16_f32 v30, v24, v25
	v_cvt_pk_bf16_f32 v31, v26, v27
	s_add_u32 s100, s16, 0x280000
	s_addc_u32 s101, s17, 0
	global_store_dwordx4 v239, v[28:31], s[100:101]
	s_waitcnt vmcnt(10)
; __device__ __forceinline__ unsigned cvt_pk_bf16(float lo, float hi) { unsigned r; asm volatile("v_cvt_pk_bf16_f32 %0, %1, %2" : "=v"(r) : "v"(lo), "v"(hi)); return r; }
; __device__ __forceinline__ float bf_lo(unsigned w) { return __uint_as_float(w << 16); }
; __device__ __forceinline__ float bf_hi(unsigned w) { return __uint_as_float(w & 0xffff0000u); }
;     __device__ __forceinline__ void operator()(const f32x4 (&acc)[2][2][4][2], const Unit& u, int wr, int wc, int fr, int fq) const {
;     ...
;                 for (int bj = 0; bj < 2; ++bj) { const u32x4 yv = *(const u32x4*)(YA + offy + (size_t)bj * 8 * SEQ * 16), zv = *(const u32x4*)(SZ + off + bj * HALF);
;                     const i32x4 q0 = __builtin_bit_cast(i32x4, acc[ai][bj][m][0]), q1 = __builtin_bit_cast(i32x4, acc[ai][bj][m][1]);
;                     const f32x4 g0 = (f32x4){(float)q0[0], (float)q0[1], (float)q0[2], (float)q0[3]} * GATE_DEQ + bv[bj][0], g1 = (f32x4){(float)q1[0], (float)q1[1], (float)q1[2], (float)q1[3]} * GATE_DEQ + bv[bj][1];
;                     float o[8];
;                     o[0] = bf_lo(yv.x) * bf_lo(zv.x) * fast_sigmoid(g0[0]); o[1] = bf_hi(yv.x) * bf_hi(zv.x) * fast_sigmoid(g0[1]);
;                     o[2] = bf_lo(yv.y) * bf_lo(zv.y) * fast_sigmoid(g0[2]); o[3] = bf_hi(yv.y) * bf_hi(zv.y) * fast_sigmoid(g0[3]);
;                     o[4] = bf_lo(yv.z) * bf_lo(zv.z) * fast_sigmoid(g1[0]); o[5] = bf_hi(yv.z) * bf_hi(zv.z) * fast_sigmoid(g1[1]);
;                     o[6] = bf_lo(yv.w) * bf_lo(zv.w) * fast_sigmoid(g1[2]); o[7] = bf_hi(yv.w) * bf_hi(zv.w) * fast_sigmoid(g1[3]);
;                     u32x4 w; w.x = cvt_pk_bf16(o[0], o[1]); w.y = cvt_pk_bf16(o[2], o[3]); w.z = cvt_pk_bf16(o[4], o[5]); w.w = cvt_pk_bf16(o[6], o[7]);
;                     *(u32x4*)(V + off + bj * HALF) = w; } }
; template <class Epi, class Sched>
; __device__ __forceinline__ void gemm_phase(PG8_LAS unsigned char* lds, const Gemm g, const Sched& S, const Epi& E, int wave_) {
;     ...
;         if (!has_next) break;
; #pragma unroll
;         for (int a = 0; a < 2; ++a)
; #pragma unroll
;             for (int b = 0; b < 2; ++b)
; #pragma unroll
;                 for (int m = 0; m < 4; ++m)
; #pragma unroll
;                     for (int n = 0; n < 2; ++n) acc[a][b][m][n] = (f32x4){0.f, 0.f, 0.f, 0.f};
;         cur = nxt; cA = nA; cB = nB; ++ui;
;         if (wr == 1) PG8_BAR;
	v_lshlrev_b32_e32 v168, 16, v152
	v_and_b32_e32 v169, 0xffff0000, v152
	v_lshlrev_b32_e32 v188, 16, v156
	v_and_b32_e32 v189, 0xffff0000, v156
	v_pk_mul_f32 v[168:169], v[168:169], v[188:189]
	v_pk_mul_f32 v[20:21], v[168:169], v[20:21]
	v_lshlrev_b32_e32 v170, 16, v153
	v_and_b32_e32 v171, 0xffff0000, v153
	v_lshlrev_b32_e32 v190, 16, v157
	v_and_b32_e32 v191, 0xffff0000, v157
	v_pk_mul_f32 v[170:171], v[170:171], v[190:191]
	v_pk_mul_f32 v[22:23], v[170:171], v[22:23]
	v_lshlrev_b32_e32 v168, 16, v154
	v_and_b32_e32 v169, 0xffff0000, v154
	v_lshlrev_b32_e32 v188, 16, v158
	v_and_b32_e32 v189, 0xffff0000, v158
	v_pk_mul_f32 v[168:169], v[168:169], v[188:189]
	v_pk_mul_f32 v[16:17], v[168:169], v[16:17]
	v_lshlrev_b32_e32 v170, 16, v155
	v_and_b32_e32 v171, 0xffff0000, v155
	v_lshlrev_b32_e32 v190, 16, v159
	v_and_b32_e32 v191, 0xffff0000, v159
	v_pk_mul_f32 v[170:171], v[170:171], v[190:191]
	v_pk_mul_f32 v[18:19], v[170:171], v[18:19]
	v_cvt_pk_bf16_f32 v20, v20, v21
	v_cvt_pk_bf16_f32 v21, v22, v23
	v_cvt_pk_bf16_f32 v22, v16, v17
	v_cvt_pk_bf16_f32 v23, v18, v19
	global_store_dwordx4 v239, v[20:23], s[100:101] offset:256
	s_waitcnt vmcnt(8)
	v_lshlrev_b32_e32 v168, 16, v160
	v_and_b32_e32 v169, 0xffff0000, v160
	v_lshlrev_b32_e32 v188, 16, v164
	v_and_b32_e32 v189, 0xffff0000, v164
	v_pk_mul_f32 v[168:169], v[168:169], v[188:189]
	v_pk_mul_f32 v[12:13], v[168:169], v[12:13]
	v_lshlrev_b32_e32 v170, 16, v161
	v_and_b32_e32 v171, 0xffff0000, v161
	v_lshlrev_b32_e32 v190, 16, v165
	v_and_b32_e32 v191, 0xffff0000, v165
	v_pk_mul_f32 v[170:171], v[170:171], v[190:191]
	v_pk_mul_f32 v[14:15], v[170:171], v[14:15]
	v_lshlrev_b32_e32 v168, 16, v162
	v_and_b32_e32 v169, 0xffff0000, v162
	v_lshlrev_b32_e32 v188, 16, v166
	v_and_b32_e32 v189, 0xffff0000, v166
	v_pk_mul_f32 v[168:169], v[168:169], v[188:189]
	v_pk_mul_f32 v[8:9], v[168:169], v[8:9]
	v_lshlrev_b32_e32 v170, 16, v163
	v_and_b32_e32 v171, 0xffff0000, v163
	v_lshlrev_b32_e32 v190, 16, v167
	v_and_b32_e32 v191, 0xffff0000, v167
	v_pk_mul_f32 v[170:171], v[170:171], v[190:191]
	v_pk_mul_f32 v[10:11], v[170:171], v[10:11]
	v_cvt_pk_bf16_f32 v12, v12, v13
	v_cvt_pk_bf16_f32 v13, v14, v15
	v_cvt_pk_bf16_f32 v14, v8, v9
	v_cvt_pk_bf16_f32 v15, v10, v11
	s_add_u32 s100, s16, 0x2c0000
	s_addc_u32 s101, s17, 0
	global_store_dwordx4 v239, v[12:15], s[100:101]
	s_waitcnt vmcnt(6)
	v_lshlrev_b32_e32 v168, 16, v172
	v_and_b32_e32 v169, 0xffff0000, v172
	v_lshlrev_b32_e32 v188, 16, v180
	v_and_b32_e32 v189, 0xffff0000, v180
	v_pk_mul_f32 v[168:169], v[168:169], v[188:189]
	v_pk_mul_f32 v[4:5], v[168:169], v[4:5]
	v_lshlrev_b32_e32 v170, 16, v173
	v_and_b32_e32 v171, 0xffff0000, v173
	v_lshlrev_b32_e32 v190, 16, v181
	v_and_b32_e32 v191, 0xffff0000, v181
	v_pk_mul_f32 v[170:171], v[170:171], v[190:191]
	v_pk_mul_f32 v[6:7], v[170:171], v[6:7]
	v_lshlrev_b32_e32 v168, 16, v174
	v_and_b32_e32 v169, 0xffff0000, v174
	v_lshlrev_b32_e32 v188, 16, v182
	v_and_b32_e32 v189, 0xffff0000, v182
	v_pk_mul_f32 v[168:169], v[168:169], v[188:189]
	v_pk_mul_f32 v[0:1], v[168:169], v[0:1]
	v_lshlrev_b32_e32 v170, 16, v175
	v_and_b32_e32 v171, 0xffff0000, v175
	v_lshlrev_b32_e32 v190, 16, v183
	v_and_b32_e32 v191, 0xffff0000, v183
	v_pk_mul_f32 v[170:171], v[170:171], v[190:191]
	v_pk_mul_f32 v[2:3], v[170:171], v[2:3]
	v_cvt_pk_bf16_f32 v4, v4, v5
	v_cvt_pk_bf16_f32 v5, v6, v7
	v_cvt_pk_bf16_f32 v6, v0, v1
	v_cvt_pk_bf16_f32 v7, v2, v3
	global_store_dwordx4 v239, v[4:7], s[100:101] offset:256
	s_andn2_b64 vcc, exec, s[42:43]
	s_mov_b64 s[42:43], -1
	s_cbranch_vccnz .LBB0_483
	s_andn2_b64 vcc, exec, s[4:5]
	s_cbranch_vccnz .LBB0_482
	s_barrier
	s_branch .LBB0_482
